# GEMM3 epilogue: every 16-byte ACT store split in two 8-byte stores, the first issued in the first epilogue pass as soon as its pair is converted (store drain starts half an epilogue earlier)
# speedup vs baseline: 1.0021x; 1.0009x over previous
; #define PG8_LAS __attribute__((address_space(3)))
;     __device__ __forceinline__ void operator()(const f32x4 (&acc)[2][2][4][2], const Unit& u, int wr, int wc, int fr, int fq) const {
;     ...
;         for (int n = 0; n < 2; ++n) {
;             const f32x4 w0 = *(const PG8_LAS f32x4*)(T + jl + 4 * n), w1 = *(const PG8_LAS f32x4*)(T + 128 + jl + 4 * n), w2 = *(const PG8_LAS f32x4*)(T + 256 + jl + 4 * n), bb = *(const PG8_LAS f32x4*)(T + 384 + jl + 4 * n);
; #pragma unroll
;             for (int ai = 0; ai < 2; ++ai) {
;                 const PG8_LAS float* RS = E + 1024 + ai * HALF + wr * 64 + fr;
;                 f32x4 bm1 = (f32x4){0.f, 0.f, 0.f, 0.f}, bm2 = bm1;
;                 if (!sample && (wr == 1 || ai == 1)) { const int sa = (wr == 1) ? ai : 0, sw = (wr == 1) ? 0 : 1;
;                     bm2 = *(const PG8_LAS f32x4*)(E + ((sa * 2 + sw) * 2 + 0) * 128 + jl + 4 * n); bm1 = *(const PG8_LAS f32x4*)(E + ((sa * 2 + sw) * 2 + 1) * 128 + jl + 4 * n); }
; #pragma unroll
;                 for (int m = 0; m < 4; ++m) {
;                     const int r = u.pm * BM + ai * HALF + wr * 64 + m * 16 + fr;
;                     const float rsm = RS[16 * m]; const f32x4 g = acc[ai][0][m][n] * rsm, uu = acc[ai][1][m][n] * rsm; f32x4 p1, p2, av;
;                     if (!sample) {
; #pragma unroll
;                         for (int e = 0; e < 4; ++e) { float o1, o2;
;                             if (m == 0) { o1 = bm1[e]; o2 = (fr == 0) ? bm2[e] : bm1[e]; } else { const float gp = acc[ai][0][m > 0 ? m - 1 : 0][n][e] * RS[16 * (m > 0 ? m - 1 : 0)]; o1 = dpp_ror1(gp); o2 = dpp_ror2(gp); }
;                             p1[e] = dpp_shr1(o1, g[e]); p2[e] = dpp_shr2(o2, g[e]); }
;                         if (ai == 0 && wr == 0 && m == 0 && fr < 2 && (u.pm & 7) != 0) {
;                             *(f32x4*)(fix + ((size_t)(72 + u.pm * 2 + fr)) * DFF + j0 + 4 * n) = g; *(f32x4*)(fix + ((size_t)(144 + u.pm * 2 + fr)) * DFF + j0 + 4 * n) = uu; }
;                     } else {
;                         const int t = fr & 7, bs = (r - MP) >> 3; f32x4 s0 = (f32x4){0.f, 0.f, 0.f, 0.f}, s1 = s0;
;                         if (t < 2) { s0 = *(const f32x4*)(st_ffn + ((size_t)bs * 2 + 0) * DFF + j0 + 4 * n); s1 = *(const f32x4*)(st_ffn + ((size_t)bs * 2 + 1) * DFF + j0 + 4 * n); }
.LBB0_747:
	s_or_b64 exec, exec, s[6:7]
	v_lshl_add_u32 v187, v186, 2, s28
	ds_read_b32 v188, v187
	v_and_b32_e32 v150, 7, v186
	v_add_u32_e32 v217, s97, v186
	s_mul_i32 s98, s76, s60
	v_ashrrev_i32_e32 v238, 6, v184
	v_add_u32_e32 v238, s98, v238
	v_ashrrev_i32_e32 v239, 31, v238
	v_lshlrev_b64 v[238:239], 15, v[238:239]
	v_lshl_add_u64 v[238:239], s[40:41], 0, v[238:239]
	v_and_b32_e32 v240, 56, v216
	v_lshlrev_b32_e32 v240, 1, v240
	v_mov_b32_e32 v241, 0
	v_lshl_add_u64 v[238:239], v[238:239], 0, v[240:241]
	v_cmp_gt_u32_e64 s[14:15], 2, v150
	v_ashrrev_i32_e32 v185, 31, v184
	v_cmp_eq_u32_e64 s[10:11], 0, v150
	v_cmp_lt_u32_e64 s[6:7], 1, v150
	v_cmp_eq_u32_e64 s[8:9], 1, v150
	v_cmp_lt_u32_e64 s[12:13], 5, v150
	v_add_u32_e32 v178, -6, v150
	v_cmp_eq_u32_e64 s[18:19], 0, v186
	v_cmp_lt_i32_e64 s[20:21], 1, v186
	s_waitcnt lgkmcnt(0)
	v_pk_mul_f32 v[152:153], v[148:149], v[188:189] op_sel_hi:[1,0]
	v_pk_mul_f32 v[150:151], v[146:147], v[188:189] op_sel_hi:[1,0]
	s_and_b64 vcc, exec, s[22:23]
	s_cbranch_vccz .LBB0_753
	s_add_i32 s16, s74, 0xffffe000
	v_add_u32_e32 v162, s16, v217
	v_ashrrev_i32_e32 v192, 3, v162
	v_mov_b32_e32 v162, 0
	v_mov_b32_e32 v163, 0
	v_mov_b32_e32 v164, 0
	v_mov_b32_e32 v165, 0
	v_mov_b32_e32 v166, 0
	v_mov_b32_e32 v167, 0
	v_mov_b32_e32 v168, 0
	v_mov_b32_e32 v169, 0
	s_and_saveexec_b64 s[16:17], s[14:15]
	s_cbranch_execz .LBB0_750
	v_mov_b64_e32 v[162:163], s[36:37]
	v_mad_i64_i32 v[162:163], s[82:83], v192, s53, v[162:163]
	v_lshl_add_u64 v[162:163], v[184:185], 2, v[162:163]
	v_add_co_u32_e32 v166, vcc, 0xa000, v162
	s_nop 1
	v_addc_co_u32_e32 v167, vcc, 0, v163, vcc
	s_mov_b64 s[98:99], 0x2b000
	v_lshl_add_u64 v[246:247], v[162:163], 0, s[98:99]
	global_load_dword v248, v[246:247], off
	s_mov_b64 s[98:99], 0x35c00
	v_lshl_add_u64 v[246:247], v[162:163], 0, s[98:99]
	global_load_dword v248, v[246:247], off
	s_mov_b64 s[98:99], 0x56000
	v_lshl_add_u64 v[246:247], v[162:163], 0, s[98:99]
	global_load_dword v248, v[246:247], off
	s_mov_b64 s[98:99], 0x60c00
	v_lshl_add_u64 v[246:247], v[162:163], 0, s[98:99]
	global_load_dword v248, v[246:247], off
	s_mov_b64 s[98:99], 0x81000
	v_lshl_add_u64 v[246:247], v[162:163], 0, s[98:99]
	global_load_dword v248, v[246:247], off
	s_mov_b64 s[98:99], 0x8bc00
	v_lshl_add_u64 v[246:247], v[162:163], 0, s[98:99]
	global_load_dword v248, v[246:247], off
	s_mov_b64 s[98:99], 0x158000
	v_lshl_add_u64 v[246:247], v[162:163], 0, s[98:99]
	global_load_dword v248, v[246:247], off
	s_mov_b64 s[98:99], 0x162c00
	v_lshl_add_u64 v[246:247], v[162:163], 0, s[98:99]
	global_load_dword v248, v[246:247], off
	s_mov_b64 s[98:99], 0x183000
	v_lshl_add_u64 v[246:247], v[162:163], 0, s[98:99]
	global_load_dword v248, v[246:247], off
	s_mov_b64 s[98:99], 0x18dc00
	v_lshl_add_u64 v[246:247], v[162:163], 0, s[98:99]
	global_load_dword v248, v[246:247], off
	s_mov_b64 s[98:99], 0x1ae000
	v_lshl_add_u64 v[246:247], v[162:163], 0, s[98:99]
	global_load_dword v248, v[246:247], off
	s_mov_b64 s[98:99], 0x1b8c00
	v_lshl_add_u64 v[246:247], v[162:163], 0, s[98:99]
	global_load_dword v248, v[246:247], off
	s_mov_b64 s[98:99], 0x1d9000
	v_lshl_add_u64 v[246:247], v[162:163], 0, s[98:99]
	global_load_dword v248, v[246:247], off
	s_mov_b64 s[98:99], 0x1e3c00
	v_lshl_add_u64 v[246:247], v[162:163], 0, s[98:99]
	global_load_dword v248, v[246:247], off
	global_load_dwordx4 v[162:165], v[162:163], off
	s_nop 0
	global_load_dwordx4 v[166:169], v[166:167], off offset:3072

; __device__ __forceinline__ unsigned cvt_pk_bf16(float lo, float hi) { unsigned r; asm volatile("v_cvt_pk_bf16_f32 %0, %1, %2" : "=v"(r) : "v"(lo), "v"(hi)); return r; }
;     __device__ __forceinline__ void operator()(const f32x4 (&acc)[2][2][4][2], const Unit& u, int wr, int wc, int fr, int fq) const {
;     ...
;                     const float rsm = RS[16 * m]; const f32x4 g = acc[ai][0][m][n] * rsm, uu = acc[ai][1][m][n] * rsm; f32x4 p1, p2, av;
;                     if (!sample) {
; #pragma unroll
;                         for (int e = 0; e < 4; ++e) { float o1, o2;
;                             if (m == 0) { o1 = bm1[e]; o2 = (fr == 0) ? bm2[e] : bm1[e]; } else { const float gp = acc[ai][0][m > 0 ? m - 1 : 0][n][e] * RS[16 * (m > 0 ? m - 1 : 0)]; o1 = dpp_ror1(gp); o2 = dpp_ror2(gp); }
;                             p1[e] = dpp_shr1(o1, g[e]); p2[e] = dpp_shr2(o2, g[e]); }
;                         if (ai == 0 && wr == 0 && m == 0 && fr < 2 && (u.pm & 7) != 0) {
;                             *(f32x4*)(fix + ((size_t)(72 + u.pm * 2 + fr)) * DFF + j0 + 4 * n) = g; *(f32x4*)(fix + ((size_t)(144 + u.pm * 2 + fr)) * DFF + j0 + 4 * n) = uu; }
;                     } else {
;                         const int t = fr & 7, bs = (r - MP) >> 3; f32x4 s0 = (f32x4){0.f, 0.f, 0.f, 0.f}, s1 = s0;
;                         if (t < 2) { s0 = *(const f32x4*)(st_ffn + ((size_t)bs * 2 + 0) * DFF + j0 + 4 * n); s1 = *(const f32x4*)(st_ffn + ((size_t)bs * 2 + 1) * DFF + j0 + 4 * n); }
; #pragma unroll
;                         for (int e = 0; e < 4; ++e) { const float a1 = dpp_shr1(0.f, g[e]), a2 = dpp_shr2(0.f, g[e]); p1[e] = (t >= 1) ? a1 : s1[e]; p2[e] = (t >= 2) ? a2 : (t == 1 ? s1[e] : s0[e]); }
;                         if (t >= 6) *(f32x4*)(out + O_SFFN + ((size_t)bs * 2 + (t - 6)) * DFF + j0 + 4 * n) = g;
;                     }
;                     const f32x4 gc = bb + w0 * p2 + w1 * p1 + w2 * g;
; #pragma unroll
;                     for (int e = 0; e < 4; ++e) av[e] = silu_e(gc[e]) * uu[e];
;                     if (n == 0) { keep[ai][m].x = cvt_pk_bf16(av[0], av[1]); keep[ai][m].y = cvt_pk_bf16(av[2], av[3]); }
;                     else { u32x4e w; w.x = keep[ai][m].x; w.y = keep[ai][m].y; w.z = cvt_pk_bf16(av[0], av[1]); w.w = cvt_pk_bf16(av[2], av[3]); *(u32x4e*)(ACT + act_off(r, j0)) = w; }
.LBB0_760:
	s_or_b64 exec, exec, s[84:85]
	v_fma_f32 v154, v141, v167, v129
	v_fmac_f32_e32 v154, v137, v168
	v_fmac_f32_e32 v154, v133, v153
	v_mul_f32_e32 v153, 0xbfb8aa3b, v154
	v_exp_f32_e32 v153, v153
	v_fma_f32 v155, v140, v164, v128
	v_fmac_f32_e32 v155, v136, v222
	v_fmac_f32_e32 v155, v132, v152
	v_add_f32_e32 v152, 1.0, v153
	v_mul_f32_e32 v153, 0xbfb8aa3b, v155
	v_exp_f32_e32 v153, v153
	v_rcp_f32_e32 v152, v152
	v_add_u32_e32 v164, 16, v217
	s_andn2_b64 vcc, exec, s[22:23]
	v_add_f32_e32 v153, 1.0, v153
	v_mul_f32_e32 v152, v154, v152
	v_mul_f32_e32 v121, v121, v152
	v_rcp_f32_e32 v152, v153
	v_fma_f32 v153, v139, v163, v127
	v_fmac_f32_e32 v153, v135, v193
	v_fma_f32 v154, v138, v162, v126
	v_fmac_f32_e32 v153, v131, v151
	v_fmac_f32_e32 v154, v134, v192
	v_mul_f32_e32 v151, 0xbfb8aa3b, v153
	v_fmac_f32_e32 v154, v130, v150
	v_exp_f32_e32 v151, v151
	v_mul_f32_e32 v150, 0xbfb8aa3b, v154
	v_exp_f32_e32 v150, v150
	v_mul_f32_e32 v152, v155, v152
	v_add_f32_e32 v151, 1.0, v151
	v_rcp_f32_e32 v151, v151
	v_add_f32_e32 v150, 1.0, v150
	v_rcp_f32_e32 v150, v150
	v_mul_f32_e32 v152, v120, v152
	v_mul_f32_e32 v120, v153, v151
	v_mul_f32_e32 v119, v119, v120
	v_mul_f32_e32 v120, v154, v150
	v_mul_f32_e32 v118, v118, v120
	v_cvt_pk_bf16_f32 v120, v118, v119
	v_cvt_pk_bf16_f32 v121, v152, v121
	v_add_u32_e32 v240, 0, v217
	v_lshlrev_b32_e32 v240, 7, v240
	v_and_b32_e32 v240, 0x7f80, v240
	v_mov_b32_e32 v241, 0
	v_lshl_add_u64 v[240:241], v[238:239], 0, v[240:241]
	global_store_dwordx2 v[240:241], v[120:121], off
	ds_read_b32 v118, v187 offset:64
	s_waitcnt lgkmcnt(0)
	v_pk_mul_f32 v[152:153], v[124:125], v[118:119] op_sel_hi:[1,0]
	v_pk_mul_f32 v[150:151], v[122:123], v[118:119] op_sel_hi:[1,0]
	v_cndmask_b32_e64 v119, 0, 1, s[22:23]
	v_cmp_ne_u32_e64 s[16:17], 1, v119
	s_mov_b64 s[22:23], -1
	s_cbranch_vccnz .LBB0_766
	s_add_i32 s22, s74, 0xffffe000
	v_add_u32_e32 v119, s22, v164
	v_ashrrev_i32_e32 v162, 3, v119
	v_mov_b32_e32 v154, 0
	v_mov_b32_e32 v155, 0
	v_mov_b32_e32 v156, 0
	v_mov_b32_e32 v157, 0
	v_mov_b32_e32 v158, 0
	v_mov_b32_e32 v159, 0
	v_mov_b32_e32 v160, 0
	v_mov_b32_e32 v161, 0
	s_and_saveexec_b64 s[22:23], s[14:15]
	s_cbranch_execz .LBB0_763
	v_mov_b64_e32 v[154:155], s[36:37]
	v_mad_i64_i32 v[154:155], s[82:83], v162, s53, v[154:155]
	v_lshl_add_u64 v[154:155], v[184:185], 2, v[154:155]
	v_add_co_u32_e32 v158, vcc, 0xa000, v154
	s_nop 1
	v_addc_co_u32_e32 v159, vcc, 0, v155, vcc
	global_load_dwordx4 v[154:157], v[154:155], off
	s_nop 0
	global_load_dwordx4 v[158:161], v[158:159], off offset:3072

; __device__ __forceinline__ unsigned cvt_pk_bf16(float lo, float hi) { unsigned r; asm volatile("v_cvt_pk_bf16_f32 %0, %1, %2" : "=v"(r) : "v"(lo), "v"(hi)); return r; }
;     __device__ __forceinline__ void operator()(const f32x4 (&acc)[2][2][4][2], const Unit& u, int wr, int wc, int fr, int fq) const {
;     ...
;                     const float rsm = RS[16 * m]; const f32x4 g = acc[ai][0][m][n] * rsm, uu = acc[ai][1][m][n] * rsm; f32x4 p1, p2, av;
;                     if (!sample) {
; #pragma unroll
;                         for (int e = 0; e < 4; ++e) { float o1, o2;
;                             if (m == 0) { o1 = bm1[e]; o2 = (fr == 0) ? bm2[e] : bm1[e]; } else { const float gp = acc[ai][0][m > 0 ? m - 1 : 0][n][e] * RS[16 * (m > 0 ? m - 1 : 0)]; o1 = dpp_ror1(gp); o2 = dpp_ror2(gp); }
;                             p1[e] = dpp_shr1(o1, g[e]); p2[e] = dpp_shr2(o2, g[e]); }
;                         if (ai == 0 && wr == 0 && m == 0 && fr < 2 && (u.pm & 7) != 0) {
;                             *(f32x4*)(fix + ((size_t)(72 + u.pm * 2 + fr)) * DFF + j0 + 4 * n) = g; *(f32x4*)(fix + ((size_t)(144 + u.pm * 2 + fr)) * DFF + j0 + 4 * n) = uu; }
;                     } else {
;                         const int t = fr & 7, bs = (r - MP) >> 3; f32x4 s0 = (f32x4){0.f, 0.f, 0.f, 0.f}, s1 = s0;
;                         if (t < 2) { s0 = *(const f32x4*)(st_ffn + ((size_t)bs * 2 + 0) * DFF + j0 + 4 * n); s1 = *(const f32x4*)(st_ffn + ((size_t)bs * 2 + 1) * DFF + j0 + 4 * n); }
; #pragma unroll
;                         for (int e = 0; e < 4; ++e) { const float a1 = dpp_shr1(0.f, g[e]), a2 = dpp_shr2(0.f, g[e]); p1[e] = (t >= 1) ? a1 : s1[e]; p2[e] = (t >= 2) ? a2 : (t == 1 ? s1[e] : s0[e]); }
;                         if (t >= 6) *(f32x4*)(out + O_SFFN + ((size_t)bs * 2 + (t - 6)) * DFF + j0 + 4 * n) = g;
;                     }
;                     const f32x4 gc = bb + w0 * p2 + w1 * p1 + w2 * g;
; #pragma unroll
;                     for (int e = 0; e < 4; ++e) av[e] = silu_e(gc[e]) * uu[e];
;                     if (n == 0) { keep[ai][m].x = cvt_pk_bf16(av[0], av[1]); keep[ai][m].y = cvt_pk_bf16(av[2], av[3]); }
;                     else { u32x4e w; w.x = keep[ai][m].x; w.y = keep[ai][m].y; w.z = cvt_pk_bf16(av[0], av[1]); w.w = cvt_pk_bf16(av[2], av[3]); *(u32x4e*)(ACT + act_off(r, j0)) = w; }
.LBB0_768:
	v_fma_f32 v148, v141, v157, v129
	v_fmac_f32_e32 v148, v137, v160
	v_fmac_f32_e32 v148, v133, v153
	v_mul_f32_e32 v146, 0xbfb8aa3b, v148
	v_exp_f32_e32 v149, v146
	v_mov_b32_e32 v146, v118
	v_mov_b32_e32 v147, v118
	v_pk_mul_f32 v[144:145], v[144:145], v[146:147]
	v_add_f32_e32 v146, 1.0, v149
	v_rcp_f32_e32 v146, v146
	v_fma_f32 v147, v140, v156, v128
	v_fmac_f32_e32 v147, v136, v159
	v_mov_b32_e32 v119, v118
	v_fmac_f32_e32 v147, v132, v152
	v_mul_f32_e32 v149, 0xbfb8aa3b, v147
	v_pk_mul_f32 v[118:119], v[142:143], v[118:119]
	v_mul_f32_e32 v142, v148, v146
	v_exp_f32_e32 v149, v149
	v_mul_f32_e32 v142, v145, v142
	v_fma_f32 v145, v139, v155, v127
	v_fmac_f32_e32 v145, v135, v158
	v_fma_f32 v148, v138, v154, v126
	v_fmac_f32_e32 v145, v131, v151
	v_fmac_f32_e32 v148, v134, v162
	v_mul_f32_e32 v146, 0xbfb8aa3b, v145
	v_fmac_f32_e32 v148, v130, v150
	v_add_f32_e32 v143, 1.0, v149
	v_exp_f32_e32 v146, v146
	v_mul_f32_e32 v149, 0xbfb8aa3b, v148
	v_rcp_f32_e32 v143, v143
	v_exp_f32_e32 v149, v149
	v_add_f32_e32 v146, 1.0, v146
	v_rcp_f32_e32 v146, v146
	v_mul_f32_e32 v143, v147, v143
	v_add_f32_e32 v147, 1.0, v149
	v_rcp_f32_e32 v147, v147
	v_mul_f32_e32 v143, v144, v143
	v_mul_f32_e32 v144, v145, v146
	v_mul_f32_e32 v119, v119, v144
	v_mul_f32_e32 v144, v148, v147
	v_mul_f32_e32 v118, v118, v144
	v_cvt_pk_bf16_f32 v118, v118, v119
	v_cvt_pk_bf16_f32 v119, v143, v142
	v_add_u32_e32 v240, 16, v217
	v_lshlrev_b32_e32 v240, 7, v240
	v_and_b32_e32 v240, 0x7f80, v240
	v_mov_b32_e32 v241, 0
	v_lshl_add_u64 v[240:241], v[238:239], 0, v[240:241]
	global_store_dwordx2 v[240:241], v[118:119], off
	ds_read_b32 v154, v187 offset:128
	v_add_u32_e32 v158, 32, v217
	s_and_b64 vcc, exec, s[16:17]
	s_mov_b64 s[22:23], -1
	s_waitcnt lgkmcnt(0)
	v_pk_mul_f32 v[144:145], v[108:109], v[154:155] op_sel_hi:[1,0]
	v_pk_mul_f32 v[142:143], v[106:107], v[154:155] op_sel_hi:[1,0]
	s_cbranch_vccnz .LBB0_774
	s_add_i32 s22, s74, 0xffffe000
	v_add_u32_e32 v146, s22, v158
	v_ashrrev_i32_e32 v156, 3, v146
	v_mov_b32_e32 v146, 0
	v_mov_b32_e32 v147, 0
	v_mov_b32_e32 v148, 0
	v_mov_b32_e32 v149, 0
	v_mov_b32_e32 v150, 0
	v_mov_b32_e32 v151, 0
	v_mov_b32_e32 v152, 0
	v_mov_b32_e32 v153, 0
	s_and_saveexec_b64 s[22:23], s[14:15]
	s_cbranch_execz .LBB0_771
	v_mov_b64_e32 v[146:147], s[36:37]
	v_mad_i64_i32 v[146:147], s[82:83], v156, s53, v[146:147]
	v_lshl_add_u64 v[146:147], v[184:185], 2, v[146:147]
	v_add_co_u32_e32 v150, vcc, 0xa000, v146
	s_nop 1
	v_addc_co_u32_e32 v151, vcc, 0, v147, vcc
	global_load_dwordx4 v[146:149], v[146:147], off
	s_nop 0
	global_load_dwordx4 v[150:153], v[150:151], off offset:3072

; __device__ __forceinline__ unsigned cvt_pk_bf16(float lo, float hi) { unsigned r; asm volatile("v_cvt_pk_bf16_f32 %0, %1, %2" : "=v"(r) : "v"(lo), "v"(hi)); return r; }
;     __device__ __forceinline__ void operator()(const f32x4 (&acc)[2][2][4][2], const Unit& u, int wr, int wc, int fr, int fq) const {
;     ...
;                     const float rsm = RS[16 * m]; const f32x4 g = acc[ai][0][m][n] * rsm, uu = acc[ai][1][m][n] * rsm; f32x4 p1, p2, av;
;                     if (!sample) {
; #pragma unroll
;                         for (int e = 0; e < 4; ++e) { float o1, o2;
;                             if (m == 0) { o1 = bm1[e]; o2 = (fr == 0) ? bm2[e] : bm1[e]; } else { const float gp = acc[ai][0][m > 0 ? m - 1 : 0][n][e] * RS[16 * (m > 0 ? m - 1 : 0)]; o1 = dpp_ror1(gp); o2 = dpp_ror2(gp); }
;                             p1[e] = dpp_shr1(o1, g[e]); p2[e] = dpp_shr2(o2, g[e]); }
;                         if (ai == 0 && wr == 0 && m == 0 && fr < 2 && (u.pm & 7) != 0) {
;                             *(f32x4*)(fix + ((size_t)(72 + u.pm * 2 + fr)) * DFF + j0 + 4 * n) = g; *(f32x4*)(fix + ((size_t)(144 + u.pm * 2 + fr)) * DFF + j0 + 4 * n) = uu; }
;                     } else {
;                         const int t = fr & 7, bs = (r - MP) >> 3; f32x4 s0 = (f32x4){0.f, 0.f, 0.f, 0.f}, s1 = s0;
;                         if (t < 2) { s0 = *(const f32x4*)(st_ffn + ((size_t)bs * 2 + 0) * DFF + j0 + 4 * n); s1 = *(const f32x4*)(st_ffn + ((size_t)bs * 2 + 1) * DFF + j0 + 4 * n); }
; #pragma unroll
;                         for (int e = 0; e < 4; ++e) { const float a1 = dpp_shr1(0.f, g[e]), a2 = dpp_shr2(0.f, g[e]); p1[e] = (t >= 1) ? a1 : s1[e]; p2[e] = (t >= 2) ? a2 : (t == 1 ? s1[e] : s0[e]); }
;                         if (t >= 6) *(f32x4*)(out + O_SFFN + ((size_t)bs * 2 + (t - 6)) * DFF + j0 + 4 * n) = g;
;                     }
;                     const f32x4 gc = bb + w0 * p2 + w1 * p1 + w2 * g;
; #pragma unroll
;                     for (int e = 0; e < 4; ++e) av[e] = silu_e(gc[e]) * uu[e];
;                     if (n == 0) { keep[ai][m].x = cvt_pk_bf16(av[0], av[1]); keep[ai][m].y = cvt_pk_bf16(av[2], av[3]); }
;                     else { u32x4e w; w.x = keep[ai][m].x; w.y = keep[ai][m].y; w.z = cvt_pk_bf16(av[0], av[1]); w.w = cvt_pk_bf16(av[2], av[3]); *(u32x4e*)(ACT + act_off(r, j0)) = w; }
.LBB0_776:
	v_fma_f32 v124, v141, v149, v129
	v_fmac_f32_e32 v124, v137, v152
	v_fmac_f32_e32 v124, v133, v145
	v_mul_f32_e32 v122, 0xbfb8aa3b, v124
	v_exp_f32_e32 v125, v122
	v_mov_b32_e32 v122, v154
	v_mov_b32_e32 v123, v154
	v_pk_mul_f32 v[116:117], v[116:117], v[122:123]
	v_add_f32_e32 v122, 1.0, v125
	v_rcp_f32_e32 v122, v122
	v_fma_f32 v123, v140, v148, v128
	v_fmac_f32_e32 v123, v136, v151
	v_fmac_f32_e32 v123, v132, v144
	v_mul_f32_e32 v125, 0xbfb8aa3b, v123
	v_exp_f32_e32 v125, v125
	v_mul_f32_e32 v122, v124, v122
	v_fma_f32 v124, v139, v147, v127
	v_fmac_f32_e32 v124, v135, v150
	v_fmac_f32_e32 v124, v131, v143
	v_fma_f32 v143, v138, v146, v126
	v_fmac_f32_e32 v143, v134, v156
	v_mul_f32_e32 v117, v117, v122
	v_add_f32_e32 v122, 1.0, v125
	v_mul_f32_e32 v125, 0xbfb8aa3b, v124
	v_fmac_f32_e32 v143, v130, v142
	v_rcp_f32_e32 v122, v122
	v_exp_f32_e32 v125, v125
	v_mul_f32_e32 v142, 0xbfb8aa3b, v143
	v_exp_f32_e32 v142, v142
	v_mul_f32_e32 v122, v123, v122
	v_add_f32_e32 v123, 1.0, v125
	v_rcp_f32_e32 v123, v123
	v_add_f32_e32 v125, 1.0, v142
	v_rcp_f32_e32 v125, v125
	v_mov_b32_e32 v155, v154
	v_pk_mul_f32 v[114:115], v[114:115], v[154:155]
	v_mul_f32_e32 v116, v116, v122
	v_mul_f32_e32 v122, v124, v123
	v_mul_f32_e32 v115, v115, v122
	v_mul_f32_e32 v122, v143, v125
	v_mul_f32_e32 v114, v114, v122
	v_cvt_pk_bf16_f32 v114, v114, v115
	v_cvt_pk_bf16_f32 v115, v116, v117
	v_add_u32_e32 v240, 32, v217
	v_lshlrev_b32_e32 v240, 7, v240
	v_and_b32_e32 v240, 0x7f80, v240
	v_mov_b32_e32 v241, 0
	v_lshl_add_u64 v[240:241], v[238:239], 0, v[240:241]
	global_store_dwordx2 v[240:241], v[114:115], off
	ds_read_b32 v116, v187 offset:192
	v_add_u32_e32 v152, 48, v217
	s_and_b64 vcc, exec, s[16:17]
	s_mov_b64 s[22:23], -1
	s_waitcnt lgkmcnt(0)
	v_pk_mul_f32 v[112:113], v[112:113], v[116:117] op_sel_hi:[1,0]
	v_pk_mul_f32 v[110:111], v[110:111], v[116:117] op_sel_hi:[1,0]
	s_cbranch_vccnz .LBB0_782
	s_add_i32 s22, s74, 0xffffe000
	v_add_u32_e32 v117, s22, v152
	v_ashrrev_i32_e32 v146, 3, v117
	v_mov_b32_e32 v122, 0
	v_mov_b32_e32 v123, 0
	v_mov_b32_e32 v124, 0
	v_mov_b32_e32 v125, 0
	v_mov_b32_e32 v142, 0
	v_mov_b32_e32 v143, 0
	v_mov_b32_e32 v144, 0
	v_mov_b32_e32 v145, 0
	s_and_saveexec_b64 s[22:23], s[14:15]
	s_cbranch_execz .LBB0_779
	v_mov_b64_e32 v[122:123], s[36:37]
	v_mad_i64_i32 v[122:123], s[82:83], v146, s53, v[122:123]
	v_lshl_add_u64 v[122:123], v[184:185], 2, v[122:123]
	v_add_co_u32_e32 v142, vcc, 0xa000, v122
	s_nop 1
	v_addc_co_u32_e32 v143, vcc, 0, v123, vcc
	global_load_dwordx4 v[122:125], v[122:123], off
	s_nop 0
	global_load_dwordx4 v[142:145], v[142:143], off offset:3072

; __device__ __forceinline__ float silu_e(float x) { return x * __builtin_amdgcn_rcpf(1.0f + __expf(-x)); }
;     __device__ __forceinline__ void operator()(const f32x4 (&acc)[2][2][4][2], const Unit& u, int wr, int wc, int fr, int fq) const {
;     ...
;                 if (!sample && (wr == 1 || ai == 1)) { const int sa = (wr == 1) ? ai : 0, sw = (wr == 1) ? 0 : 1;
;     ...
;                     const float rsm = RS[16 * m]; const f32x4 g = acc[ai][0][m][n] * rsm, uu = acc[ai][1][m][n] * rsm; f32x4 p1, p2, av;
;                     if (!sample) {
; #pragma unroll
;                         for (int e = 0; e < 4; ++e) { float o1, o2;
;                             if (m == 0) { o1 = bm1[e]; o2 = (fr == 0) ? bm2[e] : bm1[e]; } else { const float gp = acc[ai][0][m > 0 ? m - 1 : 0][n][e] * RS[16 * (m > 0 ? m - 1 : 0)]; o1 = dpp_ror1(gp); o2 = dpp_ror2(gp); }
;                             p1[e] = dpp_shr1(o1, g[e]); p2[e] = dpp_shr2(o2, g[e]); }
;                         if (ai == 0 && wr == 0 && m == 0 && fr < 2 && (u.pm & 7) != 0) {
;                             *(f32x4*)(fix + ((size_t)(72 + u.pm * 2 + fr)) * DFF + j0 + 4 * n) = g; *(f32x4*)(fix + ((size_t)(144 + u.pm * 2 + fr)) * DFF + j0 + 4 * n) = uu; }
;                     } else {
;                         const int t = fr & 7, bs = (r - MP) >> 3; f32x4 s0 = (f32x4){0.f, 0.f, 0.f, 0.f}, s1 = s0;
;                         if (t < 2) { s0 = *(const f32x4*)(st_ffn + ((size_t)bs * 2 + 0) * DFF + j0 + 4 * n); s1 = *(const f32x4*)(st_ffn + ((size_t)bs * 2 + 1) * DFF + j0 + 4 * n); }
; #pragma unroll
;                         for (int e = 0; e < 4; ++e) { const float a1 = dpp_shr1(0.f, g[e]), a2 = dpp_shr2(0.f, g[e]); p1[e] = (t >= 1) ? a1 : s1[e]; p2[e] = (t >= 2) ? a2 : (t == 1 ? s1[e] : s0[e]); }
;                         if (t >= 6) *(f32x4*)(out + O_SFFN + ((size_t)bs * 2 + (t - 6)) * DFF + j0 + 4 * n) = g;
;                     }
;                     const f32x4 gc = bb + w0 * p2 + w1 * p1 + w2 * g;
; #pragma unroll
;                     for (int e = 0; e < 4; ++e) av[e] = silu_e(gc[e]) * uu[e];
;                     if (n == 0) { keep[ai][m].x = cvt_pk_bf16(av[0], av[1]); keep[ai][m].y = cvt_pk_bf16(av[2], av[3]); }
;                     else { u32x4e w; w.x = keep[ai][m].x; w.y = keep[ai][m].y; w.z = cvt_pk_bf16(av[0], av[1]); w.w = cvt_pk_bf16(av[2], av[3]); *(u32x4e*)(ACT + act_off(r, j0)) = w; }
.LBB0_784:
	v_fma_f32 v108, v141, v125, v129
	v_fmac_f32_e32 v108, v137, v144
	v_fmac_f32_e32 v108, v133, v113
	v_mul_f32_e32 v106, 0xbfb8aa3b, v108
	v_exp_f32_e32 v109, v106
	v_mov_b32_e32 v106, v116
	v_mov_b32_e32 v107, v116
	v_pk_mul_f32 v[104:105], v[104:105], v[106:107]
	v_add_f32_e32 v106, 1.0, v109
	v_rcp_f32_e32 v106, v106
	v_fma_f32 v107, v140, v124, v128
	v_fmac_f32_e32 v107, v136, v143
	v_fmac_f32_e32 v107, v132, v112
	v_mul_f32_e32 v109, 0xbfb8aa3b, v107
	v_exp_f32_e32 v109, v109
	v_mul_f32_e32 v106, v108, v106
	v_fma_f32 v108, v139, v123, v127
	v_fmac_f32_e32 v108, v135, v142
	v_fmac_f32_e32 v108, v131, v111
	v_fma_f32 v111, v138, v122, v126
	v_fmac_f32_e32 v111, v134, v146
	v_mul_f32_e32 v105, v105, v106
	v_add_f32_e32 v106, 1.0, v109
	v_mul_f32_e32 v109, 0xbfb8aa3b, v108
	v_fmac_f32_e32 v111, v130, v110
	v_rcp_f32_e32 v106, v106
	v_exp_f32_e32 v109, v109
	v_mul_f32_e32 v110, 0xbfb8aa3b, v111
	v_exp_f32_e32 v110, v110
	v_mul_f32_e32 v106, v107, v106
	v_add_f32_e32 v107, 1.0, v109
	v_rcp_f32_e32 v107, v107
	v_add_f32_e32 v109, 1.0, v110
	v_rcp_f32_e32 v109, v109
	v_mov_b32_e32 v117, v116
	v_pk_mul_f32 v[102:103], v[102:103], v[116:117]
	v_mul_f32_e32 v104, v104, v106
	v_mul_f32_e32 v106, v108, v107
	v_mul_f32_e32 v103, v103, v106
	v_mul_f32_e32 v106, v111, v109
	v_mul_f32_e32 v102, v102, v106
	v_cvt_pk_bf16_f32 v102, v102, v103
	v_cvt_pk_bf16_f32 v103, v104, v105
	v_add_u32_e32 v240, 48, v217
	v_lshlrev_b32_e32 v240, 7, v240
	v_and_b32_e32 v240, 0x7f80, v240
	v_mov_b32_e32 v241, 0
	v_lshl_add_u64 v[240:241], v[238:239], 0, v[240:241]
	global_store_dwordx2 v[240:241], v[102:103], off
	v_cndmask_b32_e64 v104, 0, 1, s[80:81]
	v_mov_b32_e32 v108, 0
	v_cmp_ne_u32_e64 s[22:23], 1, v104
	s_andn2_b64 vcc, exec, s[80:81]
	v_lshl_add_u32 v153, v216, 2, v206
	v_mov_b32_e32 v109, 0
	v_mov_b32_e32 v110, 0
	v_mov_b32_e32 v111, 0
	v_mov_b32_e32 v122, 0
	v_mov_b32_e32 v123, 0
	v_mov_b32_e32 v124, 0
	v_mov_b32_e32 v125, 0
	s_cbranch_vccnz .LBB0_786
	ds_read_b128 v[108:111], v153
	ds_read_b128 v[122:125], v153 offset:512

; __device__ __forceinline__ unsigned cvt_pk_bf16(float lo, float hi) { unsigned r; asm volatile("v_cvt_pk_bf16_f32 %0, %1, %2" : "=v"(r) : "v"(lo), "v"(hi)); return r; }
;     __device__ __forceinline__ void operator()(const f32x4 (&acc)[2][2][4][2], const Unit& u, int wr, int wc, int fr, int fq) const {
;     ...
;                     const float rsm = RS[16 * m]; const f32x4 g = acc[ai][0][m][n] * rsm, uu = acc[ai][1][m][n] * rsm; f32x4 p1, p2, av;
;                     if (!sample) {
; #pragma unroll
;                         for (int e = 0; e < 4; ++e) { float o1, o2;
;                             if (m == 0) { o1 = bm1[e]; o2 = (fr == 0) ? bm2[e] : bm1[e]; } else { const float gp = acc[ai][0][m > 0 ? m - 1 : 0][n][e] * RS[16 * (m > 0 ? m - 1 : 0)]; o1 = dpp_ror1(gp); o2 = dpp_ror2(gp); }
;                             p1[e] = dpp_shr1(o1, g[e]); p2[e] = dpp_shr2(o2, g[e]); }
;                         if (ai == 0 && wr == 0 && m == 0 && fr < 2 && (u.pm & 7) != 0) {
;                             *(f32x4*)(fix + ((size_t)(72 + u.pm * 2 + fr)) * DFF + j0 + 4 * n) = g; *(f32x4*)(fix + ((size_t)(144 + u.pm * 2 + fr)) * DFF + j0 + 4 * n) = uu; }
;                     } else {
;                         const int t = fr & 7, bs = (r - MP) >> 3; f32x4 s0 = (f32x4){0.f, 0.f, 0.f, 0.f}, s1 = s0;
;                         if (t < 2) { s0 = *(const f32x4*)(st_ffn + ((size_t)bs * 2 + 0) * DFF + j0 + 4 * n); s1 = *(const f32x4*)(st_ffn + ((size_t)bs * 2 + 1) * DFF + j0 + 4 * n); }
; #pragma unroll
;                         for (int e = 0; e < 4; ++e) { const float a1 = dpp_shr1(0.f, g[e]), a2 = dpp_shr2(0.f, g[e]); p1[e] = (t >= 1) ? a1 : s1[e]; p2[e] = (t >= 2) ? a2 : (t == 1 ? s1[e] : s0[e]); }
;                         if (t >= 6) *(f32x4*)(out + O_SFFN + ((size_t)bs * 2 + (t - 6)) * DFF + j0 + 4 * n) = g;
;                     }
;                     const f32x4 gc = bb + w0 * p2 + w1 * p1 + w2 * g;
; #pragma unroll
;                     for (int e = 0; e < 4; ++e) av[e] = silu_e(gc[e]) * uu[e];
;                     if (n == 0) { keep[ai][m].x = cvt_pk_bf16(av[0], av[1]); keep[ai][m].y = cvt_pk_bf16(av[2], av[3]); }
;                     else { u32x4e w; w.x = keep[ai][m].x; w.y = keep[ai][m].y; w.z = cvt_pk_bf16(av[0], av[1]); w.w = cvt_pk_bf16(av[2], av[3]); *(u32x4e*)(ACT + act_off(r, j0)) = w; }
.LBB0_794:
	v_fma_f32 v110, v141, v144, v129
	v_fmac_f32_e32 v110, v137, v147
	v_fmac_f32_e32 v110, v133, v107
	v_mul_f32_e32 v107, 0xbfb8aa3b, v110
	v_exp_f32_e32 v107, v107
	v_mov_b32_e32 v108, v112
	v_mov_b32_e32 v109, v112
	v_pk_mul_f32 v[100:101], v[100:101], v[108:109]
	v_add_f32_e32 v107, 1.0, v107
	v_rcp_f32_e32 v107, v107
	v_fma_f32 v108, v140, v143, v128
	v_fma_f32 v109, v138, v116, v126
	v_fmac_f32_e32 v108, v136, v146
	v_mul_f32_e32 v107, v110, v107
	v_mul_f32_e32 v101, v101, v107
	v_fma_f32 v107, v139, v117, v127
	v_fmac_f32_e32 v107, v135, v142
	v_fmac_f32_e32 v109, v134, v154
	v_fmac_f32_e32 v108, v132, v106
	v_fmac_f32_e32 v107, v131, v105
	v_fmac_f32_e32 v109, v130, v104
	v_mul_f32_e32 v106, 0xbfb8aa3b, v108
	v_mul_f32_e32 v105, 0xbfb8aa3b, v107
	v_mul_f32_e32 v104, 0xbfb8aa3b, v109
	v_exp_f32_e32 v106, v106
	v_exp_f32_e32 v105, v105
	v_exp_f32_e32 v104, v104
	v_mov_b32_e32 v113, v112
	v_add_f32_e32 v106, 1.0, v106
	v_add_f32_e32 v105, 1.0, v105
	v_add_f32_e32 v104, 1.0, v104
	v_rcp_f32_e32 v106, v106
	v_rcp_f32_e32 v105, v105
	v_rcp_f32_e32 v104, v104
	v_pk_mul_f32 v[98:99], v[98:99], v[112:113]
	v_mul_f32_e32 v106, v108, v106
	v_mul_f32_e32 v105, v107, v105
	v_mul_f32_e32 v104, v109, v104
	v_mul_f32_e32 v100, v100, v106
	v_mul_f32_e32 v99, v99, v105
	v_mul_f32_e32 v98, v98, v104
	v_cvt_pk_bf16_f32 v98, v98, v99
	v_cvt_pk_bf16_f32 v99, v100, v101
	v_add_u32_e32 v240, 0x80, v217
	v_lshlrev_b32_e32 v240, 7, v240
	v_and_b32_e32 v240, 0x7f80, v240
	v_mov_b32_e32 v241, 0
	v_lshl_add_u64 v[240:241], v[238:239], 0, v[240:241]
	global_store_dwordx2 v[240:241], v[98:99], off
	ds_read_b32 v100, v150 offset:64
	v_add_u32_e32 v142, 0x90, v217
	s_and_b64 vcc, exec, s[16:17]
	s_mov_b64 s[80:81], -1
	s_waitcnt lgkmcnt(0)
	v_pk_mul_f32 v[106:107], v[88:89], v[100:101] op_sel_hi:[1,0]
	v_pk_mul_f32 v[104:105], v[86:87], v[100:101] op_sel_hi:[1,0]
	s_cbranch_vccnz .LBB0_800
	s_add_i32 s65, s74, 0xffffe000
	v_add_u32_e32 v101, s65, v142
	v_ashrrev_i32_e32 v112, 3, v101
	v_mov_b32_e32 v108, 0
	v_mov_b32_e32 v109, 0
	v_mov_b32_e32 v110, 0
	v_mov_b32_e32 v111, 0
	v_mov_b32_e32 v122, 0
	v_mov_b32_e32 v123, 0
	v_mov_b32_e32 v124, 0
	v_mov_b32_e32 v125, 0
	s_and_saveexec_b64 s[80:81], s[14:15]
	s_cbranch_execz .LBB0_797
	v_mov_b64_e32 v[108:109], s[36:37]
	v_mad_i64_i32 v[108:109], s[82:83], v112, s53, v[108:109]
	v_lshl_add_u64 v[108:109], v[184:185], 2, v[108:109]
	v_add_co_u32_e32 v116, vcc, 0xa000, v108
	s_nop 1
	v_addc_co_u32_e32 v117, vcc, 0, v109, vcc
	global_load_dwordx4 v[108:111], v[108:109], off
	s_nop 0
	global_load_dwordx4 v[122:125], v[116:117], off offset:3072

; __device__ __forceinline__ unsigned cvt_pk_bf16(float lo, float hi) { unsigned r; asm volatile("v_cvt_pk_bf16_f32 %0, %1, %2" : "=v"(r) : "v"(lo), "v"(hi)); return r; }
;     __device__ __forceinline__ void operator()(const f32x4 (&acc)[2][2][4][2], const Unit& u, int wr, int wc, int fr, int fq) const {
;     ...
;                     const float rsm = RS[16 * m]; const f32x4 g = acc[ai][0][m][n] * rsm, uu = acc[ai][1][m][n] * rsm; f32x4 p1, p2, av;
;                     if (!sample) {
; #pragma unroll
;                         for (int e = 0; e < 4; ++e) { float o1, o2;
;                             if (m == 0) { o1 = bm1[e]; o2 = (fr == 0) ? bm2[e] : bm1[e]; } else { const float gp = acc[ai][0][m > 0 ? m - 1 : 0][n][e] * RS[16 * (m > 0 ? m - 1 : 0)]; o1 = dpp_ror1(gp); o2 = dpp_ror2(gp); }
;                             p1[e] = dpp_shr1(o1, g[e]); p2[e] = dpp_shr2(o2, g[e]); }
;                         if (ai == 0 && wr == 0 && m == 0 && fr < 2 && (u.pm & 7) != 0) {
;                             *(f32x4*)(fix + ((size_t)(72 + u.pm * 2 + fr)) * DFF + j0 + 4 * n) = g; *(f32x4*)(fix + ((size_t)(144 + u.pm * 2 + fr)) * DFF + j0 + 4 * n) = uu; }
;                     } else {
;                         const int t = fr & 7, bs = (r - MP) >> 3; f32x4 s0 = (f32x4){0.f, 0.f, 0.f, 0.f}, s1 = s0;
;                         if (t < 2) { s0 = *(const f32x4*)(st_ffn + ((size_t)bs * 2 + 0) * DFF + j0 + 4 * n); s1 = *(const f32x4*)(st_ffn + ((size_t)bs * 2 + 1) * DFF + j0 + 4 * n); }
; #pragma unroll
;                         for (int e = 0; e < 4; ++e) { const float a1 = dpp_shr1(0.f, g[e]), a2 = dpp_shr2(0.f, g[e]); p1[e] = (t >= 1) ? a1 : s1[e]; p2[e] = (t >= 2) ? a2 : (t == 1 ? s1[e] : s0[e]); }
;                         if (t >= 6) *(f32x4*)(out + O_SFFN + ((size_t)bs * 2 + (t - 6)) * DFF + j0 + 4 * n) = g;
;                     }
;                     const f32x4 gc = bb + w0 * p2 + w1 * p1 + w2 * g;
; #pragma unroll
;                     for (int e = 0; e < 4; ++e) av[e] = silu_e(gc[e]) * uu[e];
;                     if (n == 0) { keep[ai][m].x = cvt_pk_bf16(av[0], av[1]); keep[ai][m].y = cvt_pk_bf16(av[2], av[3]); }
;                     else { u32x4e w; w.x = keep[ai][m].x; w.y = keep[ai][m].y; w.z = cvt_pk_bf16(av[0], av[1]); w.w = cvt_pk_bf16(av[2], av[3]); *(u32x4e*)(ACT + act_off(r, j0)) = w; }
.LBB0_802:
	v_fma_f32 v96, v141, v111, v129
	v_fmac_f32_e32 v96, v137, v117
	v_fmac_f32_e32 v96, v133, v107
	v_mul_f32_e32 v94, 0xbfb8aa3b, v96
	v_exp_f32_e32 v97, v94
	v_mov_b32_e32 v94, v100
	v_mov_b32_e32 v95, v100
	v_pk_mul_f32 v[92:93], v[92:93], v[94:95]
	v_add_f32_e32 v94, 1.0, v97
	v_fma_f32 v95, v140, v110, v128
	v_rcp_f32_e32 v94, v94
	v_fmac_f32_e32 v95, v136, v116
	v_fmac_f32_e32 v95, v132, v106
	v_mul_f32_e32 v97, 0xbfb8aa3b, v95
	v_exp_f32_e32 v97, v97
	v_mov_b32_e32 v101, v100
	v_mul_f32_e32 v94, v96, v94
	v_fma_f32 v96, v139, v109, v127
	v_pk_mul_f32 v[90:91], v[90:91], v[100:101]
	v_fmac_f32_e32 v96, v135, v113
	v_fma_f32 v100, v138, v108, v126
	v_fmac_f32_e32 v96, v131, v105
	v_fmac_f32_e32 v100, v134, v112
	v_mul_f32_e32 v93, v93, v94
	v_add_f32_e32 v94, 1.0, v97
	v_mul_f32_e32 v97, 0xbfb8aa3b, v96
	v_fmac_f32_e32 v100, v130, v104
	v_rcp_f32_e32 v94, v94
	v_exp_f32_e32 v97, v97
	v_mul_f32_e32 v101, 0xbfb8aa3b, v100
	v_exp_f32_e32 v101, v101
	v_mul_f32_e32 v94, v95, v94
	v_add_f32_e32 v95, 1.0, v97
	v_rcp_f32_e32 v95, v95
	v_add_f32_e32 v97, 1.0, v101
	v_rcp_f32_e32 v97, v97
	v_mul_f32_e32 v92, v92, v94
	v_mul_f32_e32 v94, v96, v95
	v_mul_f32_e32 v91, v91, v94
	v_mul_f32_e32 v94, v100, v97
	v_mul_f32_e32 v90, v90, v94
	v_cvt_pk_bf16_f32 v90, v90, v91
	v_cvt_pk_bf16_f32 v91, v92, v93
	v_add_u32_e32 v240, 0x90, v217
	v_lshlrev_b32_e32 v240, 7, v240
	v_and_b32_e32 v240, 0x7f80, v240
	v_mov_b32_e32 v241, 0
	v_lshl_add_u64 v[240:241], v[238:239], 0, v[240:241]
	global_store_dwordx2 v[240:241], v[90:91], off
	ds_read_b32 v96, v150 offset:128
	v_add_u32_e32 v113, 0xa0, v217
	s_and_b64 vcc, exec, s[16:17]
	s_mov_b64 s[80:81], -1
	s_waitcnt lgkmcnt(0)
	v_pk_mul_f32 v[94:95], v[76:77], v[96:97] op_sel_hi:[1,0]
	v_pk_mul_f32 v[92:93], v[74:75], v[96:97] op_sel_hi:[1,0]
	s_cbranch_vccnz .LBB0_808
	s_add_i32 s65, s74, 0xffffe000
	v_add_u32_e32 v97, s65, v113
	v_ashrrev_i32_e32 v100, 3, v97
	v_mov_b32_e32 v104, 0
	v_mov_b32_e32 v105, 0
	v_mov_b32_e32 v106, 0
	v_mov_b32_e32 v107, 0
	v_mov_b32_e32 v108, 0
	v_mov_b32_e32 v109, 0
	v_mov_b32_e32 v110, 0
	v_mov_b32_e32 v111, 0
	s_and_saveexec_b64 s[80:81], s[14:15]
	s_cbranch_execz .LBB0_805
	v_mov_b64_e32 v[104:105], s[36:37]
	v_mad_i64_i32 v[104:105], s[82:83], v100, s53, v[104:105]
	v_lshl_add_u64 v[104:105], v[184:185], 2, v[104:105]
	v_add_co_u32_e32 v108, vcc, 0xa000, v104
	s_nop 1
	v_addc_co_u32_e32 v109, vcc, 0, v105, vcc
	global_load_dwordx4 v[104:107], v[104:105], off
	s_nop 0
	global_load_dwordx4 v[108:111], v[108:109], off offset:3072

; __device__ __forceinline__ unsigned cvt_pk_bf16(float lo, float hi) { unsigned r; asm volatile("v_cvt_pk_bf16_f32 %0, %1, %2" : "=v"(r) : "v"(lo), "v"(hi)); return r; }
;     __device__ __forceinline__ void operator()(const f32x4 (&acc)[2][2][4][2], const Unit& u, int wr, int wc, int fr, int fq) const {
;     ...
;                     const float rsm = RS[16 * m]; const f32x4 g = acc[ai][0][m][n] * rsm, uu = acc[ai][1][m][n] * rsm; f32x4 p1, p2, av;
;                     if (!sample) {
; #pragma unroll
;                         for (int e = 0; e < 4; ++e) { float o1, o2;
;                             if (m == 0) { o1 = bm1[e]; o2 = (fr == 0) ? bm2[e] : bm1[e]; } else { const float gp = acc[ai][0][m > 0 ? m - 1 : 0][n][e] * RS[16 * (m > 0 ? m - 1 : 0)]; o1 = dpp_ror1(gp); o2 = dpp_ror2(gp); }
;                             p1[e] = dpp_shr1(o1, g[e]); p2[e] = dpp_shr2(o2, g[e]); }
;                         if (ai == 0 && wr == 0 && m == 0 && fr < 2 && (u.pm & 7) != 0) {
;                             *(f32x4*)(fix + ((size_t)(72 + u.pm * 2 + fr)) * DFF + j0 + 4 * n) = g; *(f32x4*)(fix + ((size_t)(144 + u.pm * 2 + fr)) * DFF + j0 + 4 * n) = uu; }
;                     } else {
;                         const int t = fr & 7, bs = (r - MP) >> 3; f32x4 s0 = (f32x4){0.f, 0.f, 0.f, 0.f}, s1 = s0;
;                         if (t < 2) { s0 = *(const f32x4*)(st_ffn + ((size_t)bs * 2 + 0) * DFF + j0 + 4 * n); s1 = *(const f32x4*)(st_ffn + ((size_t)bs * 2 + 1) * DFF + j0 + 4 * n); }
; #pragma unroll
;                         for (int e = 0; e < 4; ++e) { const float a1 = dpp_shr1(0.f, g[e]), a2 = dpp_shr2(0.f, g[e]); p1[e] = (t >= 1) ? a1 : s1[e]; p2[e] = (t >= 2) ? a2 : (t == 1 ? s1[e] : s0[e]); }
;                         if (t >= 6) *(f32x4*)(out + O_SFFN + ((size_t)bs * 2 + (t - 6)) * DFF + j0 + 4 * n) = g;
;                     }
;                     const f32x4 gc = bb + w0 * p2 + w1 * p1 + w2 * g;
; #pragma unroll
;                     for (int e = 0; e < 4; ++e) av[e] = silu_e(gc[e]) * uu[e];
;                     if (n == 0) { keep[ai][m].x = cvt_pk_bf16(av[0], av[1]); keep[ai][m].y = cvt_pk_bf16(av[2], av[3]); }
;                     else { u32x4e w; w.x = keep[ai][m].x; w.y = keep[ai][m].y; w.z = cvt_pk_bf16(av[0], av[1]); w.w = cvt_pk_bf16(av[2], av[3]); *(u32x4e*)(ACT + act_off(r, j0)) = w; }
.LBB0_810:
	v_fma_f32 v88, v141, v107, v129
	v_fmac_f32_e32 v88, v137, v109
	v_fmac_f32_e32 v88, v133, v95
	v_mul_f32_e32 v86, 0xbfb8aa3b, v88
	v_exp_f32_e32 v89, v86
	v_mov_b32_e32 v86, v96
	v_mov_b32_e32 v87, v96
	v_pk_mul_f32 v[84:85], v[84:85], v[86:87]
	v_add_f32_e32 v86, 1.0, v89
	v_rcp_f32_e32 v86, v86
	v_fma_f32 v87, v140, v106, v128
	v_fmac_f32_e32 v87, v136, v108
	v_fmac_f32_e32 v87, v132, v94
	v_mul_f32_e32 v89, 0xbfb8aa3b, v87
	v_exp_f32_e32 v89, v89
	v_mul_f32_e32 v86, v88, v86
	v_fma_f32 v88, v139, v105, v127
	v_fmac_f32_e32 v88, v135, v104
	v_fmac_f32_e32 v88, v131, v93
	v_fma_f32 v93, v138, v101, v126
	v_fmac_f32_e32 v93, v134, v100
	v_mul_f32_e32 v85, v85, v86
	v_add_f32_e32 v86, 1.0, v89
	v_mul_f32_e32 v89, 0xbfb8aa3b, v88
	v_fmac_f32_e32 v93, v130, v92
	v_rcp_f32_e32 v86, v86
	v_exp_f32_e32 v89, v89
	v_mul_f32_e32 v92, 0xbfb8aa3b, v93
	v_exp_f32_e32 v92, v92
	v_mul_f32_e32 v86, v87, v86
	v_add_f32_e32 v87, 1.0, v89
	v_rcp_f32_e32 v87, v87
	v_add_f32_e32 v89, 1.0, v92
	v_rcp_f32_e32 v89, v89
	v_mov_b32_e32 v97, v96
	v_pk_mul_f32 v[82:83], v[82:83], v[96:97]
	v_mul_f32_e32 v84, v84, v86
	v_mul_f32_e32 v86, v88, v87
	v_mul_f32_e32 v83, v83, v86
	v_mul_f32_e32 v86, v93, v89
	v_mul_f32_e32 v82, v82, v86
	v_cvt_pk_bf16_f32 v82, v82, v83
	v_cvt_pk_bf16_f32 v83, v84, v85
	v_add_u32_e32 v240, 0xa0, v217
	v_lshlrev_b32_e32 v240, 7, v240
	v_and_b32_e32 v240, 0x7f80, v240
	v_mov_b32_e32 v241, 0
	v_lshl_add_u64 v[240:241], v[238:239], 0, v[240:241]
	global_store_dwordx2 v[240:241], v[82:83], off
	ds_read_b32 v88, v150 offset:192
	v_add_u32_e32 v112, 0xb0, v217
	s_and_b64 vcc, exec, s[16:17]
	s_mov_b64 s[80:81], -1
	s_waitcnt lgkmcnt(0)
	v_pk_mul_f32 v[80:81], v[80:81], v[88:89] op_sel_hi:[1,0]
	v_pk_mul_f32 v[78:79], v[78:79], v[88:89] op_sel_hi:[1,0]
	s_cbranch_vccnz .LBB0_816
	s_add_i32 s65, s74, 0xffffe000
	v_add_u32_e32 v84, s65, v112
	v_ashrrev_i32_e32 v96, 3, v84
	v_mov_b32_e32 v84, 0
	v_mov_b32_e32 v85, 0
	v_mov_b32_e32 v86, 0
	v_mov_b32_e32 v87, 0
	v_mov_b32_e32 v92, 0
	v_mov_b32_e32 v93, 0
	v_mov_b32_e32 v94, 0
	v_mov_b32_e32 v95, 0
	s_and_saveexec_b64 s[80:81], s[14:15]
	s_cbranch_execz .LBB0_813
	v_mov_b64_e32 v[84:85], s[36:37]
	v_mad_i64_i32 v[84:85], s[82:83], v96, s53, v[84:85]
	v_lshl_add_u64 v[84:85], v[184:185], 2, v[84:85]
	v_add_co_u32_e32 v92, vcc, 0xa000, v84
	s_nop 1
	v_addc_co_u32_e32 v93, vcc, 0, v85, vcc
	global_load_dwordx4 v[84:87], v[84:85], off
	s_nop 0
	global_load_dwordx4 v[92:95], v[92:93], off offset:3072

; __device__ __forceinline__ unsigned cvt_pk_bf16(float lo, float hi) { unsigned r; asm volatile("v_cvt_pk_bf16_f32 %0, %1, %2" : "=v"(r) : "v"(lo), "v"(hi)); return r; }
;     __device__ __forceinline__ void operator()(const f32x4 (&acc)[2][2][4][2], const Unit& u, int wr, int wc, int fr, int fq) const {
;     ...
;         for (int n = 0; n < 2; ++n) {
;     ...
;                     const float rsm = RS[16 * m]; const f32x4 g = acc[ai][0][m][n] * rsm, uu = acc[ai][1][m][n] * rsm; f32x4 p1, p2, av;
;                     if (!sample) {
; #pragma unroll
;                         for (int e = 0; e < 4; ++e) { float o1, o2;
;                             if (m == 0) { o1 = bm1[e]; o2 = (fr == 0) ? bm2[e] : bm1[e]; } else { const float gp = acc[ai][0][m > 0 ? m - 1 : 0][n][e] * RS[16 * (m > 0 ? m - 1 : 0)]; o1 = dpp_ror1(gp); o2 = dpp_ror2(gp); }
;                             p1[e] = dpp_shr1(o1, g[e]); p2[e] = dpp_shr2(o2, g[e]); }
;                         if (ai == 0 && wr == 0 && m == 0 && fr < 2 && (u.pm & 7) != 0) {
;                             *(f32x4*)(fix + ((size_t)(72 + u.pm * 2 + fr)) * DFF + j0 + 4 * n) = g; *(f32x4*)(fix + ((size_t)(144 + u.pm * 2 + fr)) * DFF + j0 + 4 * n) = uu; }
;                     } else {
;                         const int t = fr & 7, bs = (r - MP) >> 3; f32x4 s0 = (f32x4){0.f, 0.f, 0.f, 0.f}, s1 = s0;
;                         if (t < 2) { s0 = *(const f32x4*)(st_ffn + ((size_t)bs * 2 + 0) * DFF + j0 + 4 * n); s1 = *(const f32x4*)(st_ffn + ((size_t)bs * 2 + 1) * DFF + j0 + 4 * n); }
; #pragma unroll
;                         for (int e = 0; e < 4; ++e) { const float a1 = dpp_shr1(0.f, g[e]), a2 = dpp_shr2(0.f, g[e]); p1[e] = (t >= 1) ? a1 : s1[e]; p2[e] = (t >= 2) ? a2 : (t == 1 ? s1[e] : s0[e]); }
;                         if (t >= 6) *(f32x4*)(out + O_SFFN + ((size_t)bs * 2 + (t - 6)) * DFF + j0 + 4 * n) = g;
;                     }
;                     const f32x4 gc = bb + w0 * p2 + w1 * p1 + w2 * g;
; #pragma unroll
;                     for (int e = 0; e < 4; ++e) av[e] = silu_e(gc[e]) * uu[e];
;                     if (n == 0) { keep[ai][m].x = cvt_pk_bf16(av[0], av[1]); keep[ai][m].y = cvt_pk_bf16(av[2], av[3]); }
;                     else { u32x4e w; w.x = keep[ai][m].x; w.y = keep[ai][m].y; w.z = cvt_pk_bf16(av[0], av[1]); w.w = cvt_pk_bf16(av[2], av[3]); *(u32x4e*)(ACT + act_off(r, j0)) = w; }
.LBB0_818:
	v_fma_f32 v76, v141, v87, v129
	v_fmac_f32_e32 v76, v137, v94
	v_fmac_f32_e32 v76, v133, v81
	v_mul_f32_e32 v74, 0xbfb8aa3b, v76
	v_exp_f32_e32 v77, v74
	v_mov_b32_e32 v74, v88
	v_mov_b32_e32 v75, v88
	v_pk_mul_f32 v[72:73], v[72:73], v[74:75]
	v_add_f32_e32 v74, 1.0, v77
	v_fma_f32 v75, v140, v86, v128
	v_rcp_f32_e32 v74, v74
	v_fmac_f32_e32 v75, v136, v93
	v_fmac_f32_e32 v75, v132, v80
	v_mul_f32_e32 v77, 0xbfb8aa3b, v75
	v_exp_f32_e32 v77, v77
	v_mul_f32_e32 v74, v76, v74
	v_fma_f32 v76, v139, v85, v127
	v_fmac_f32_e32 v76, v135, v92
	v_fmac_f32_e32 v126, v138, v84
	v_fmac_f32_e32 v76, v131, v79
	v_fmac_f32_e32 v126, v134, v96
	v_mul_f32_e32 v73, v73, v74
	v_add_f32_e32 v74, 1.0, v77
	v_mul_f32_e32 v77, 0xbfb8aa3b, v76
	v_fmac_f32_e32 v126, v130, v78
	v_rcp_f32_e32 v74, v74
	v_exp_f32_e32 v77, v77
	v_mul_f32_e32 v78, 0xbfb8aa3b, v126
	v_exp_f32_e32 v78, v78
	v_mul_f32_e32 v74, v75, v74
	v_add_f32_e32 v75, 1.0, v77
	v_rcp_f32_e32 v75, v75
	v_add_f32_e32 v77, 1.0, v78
	v_rcp_f32_e32 v77, v77
	v_mov_b32_e32 v89, v88
	v_pk_mul_f32 v[70:71], v[70:71], v[88:89]
	v_mul_f32_e32 v72, v72, v74
	v_mul_f32_e32 v74, v76, v75
	v_mul_f32_e32 v71, v71, v74
	v_mul_f32_e32 v74, v126, v77
	v_mul_f32_e32 v70, v70, v74
	v_cvt_pk_bf16_f32 v70, v70, v71
	v_cvt_pk_bf16_f32 v71, v72, v73
	v_add_u32_e32 v240, 0xb0, v217
	v_lshlrev_b32_e32 v240, 7, v240
	v_and_b32_e32 v240, 0x7f80, v240
	v_mov_b32_e32 v241, 0
	v_lshl_add_u64 v[240:241], v[238:239], 0, v[240:241]
	global_store_dwordx2 v[240:241], v[70:71], off
	ds_read_b128 v[72:75], v218 offset:16
	ds_read_b128 v[92:95], v219 offset:16
	ds_read_b128 v[86:89], v220 offset:16
	ds_read_b128 v[76:79], v221 offset:16
	v_mov_b32_e32 v126, 0
	v_mov_b32_e32 v127, 0
	v_mov_b32_e32 v128, 0
	v_mov_b32_e32 v129, 0
	v_mov_b32_e32 v108, 0
	v_mov_b32_e32 v109, 0
	v_mov_b32_e32 v110, 0
	v_mov_b32_e32 v111, 0
	s_and_saveexec_b64 s[80:81], s[78:79]
	s_cbranch_execz .LBB0_820
	v_lshl_add_u32 v80, v216, 2, s61
	ds_read_b128 v[126:129], v80 offset:16
	ds_read_b128 v[108:111], v80 offset:528

; __device__ __forceinline__ unsigned cvt_pk_bf16(float lo, float hi) { unsigned r; asm volatile("v_cvt_pk_bf16_f32 %0, %1, %2" : "=v"(r) : "v"(lo), "v"(hi)); return r; }
;     __device__ __forceinline__ void operator()(const f32x4 (&acc)[2][2][4][2], const Unit& u, int wr, int wc, int fr, int fq) const {
;     ...
;                     const float rsm = RS[16 * m]; const f32x4 g = acc[ai][0][m][n] * rsm, uu = acc[ai][1][m][n] * rsm; f32x4 p1, p2, av;
;                     if (!sample) {
; #pragma unroll
;                         for (int e = 0; e < 4; ++e) { float o1, o2;
;                             if (m == 0) { o1 = bm1[e]; o2 = (fr == 0) ? bm2[e] : bm1[e]; } else { const float gp = acc[ai][0][m > 0 ? m - 1 : 0][n][e] * RS[16 * (m > 0 ? m - 1 : 0)]; o1 = dpp_ror1(gp); o2 = dpp_ror2(gp); }
;                             p1[e] = dpp_shr1(o1, g[e]); p2[e] = dpp_shr2(o2, g[e]); }
;                         if (ai == 0 && wr == 0 && m == 0 && fr < 2 && (u.pm & 7) != 0) {
;                             *(f32x4*)(fix + ((size_t)(72 + u.pm * 2 + fr)) * DFF + j0 + 4 * n) = g; *(f32x4*)(fix + ((size_t)(144 + u.pm * 2 + fr)) * DFF + j0 + 4 * n) = uu; }
;                     } else {
;                         const int t = fr & 7, bs = (r - MP) >> 3; f32x4 s0 = (f32x4){0.f, 0.f, 0.f, 0.f}, s1 = s0;
;                         if (t < 2) { s0 = *(const f32x4*)(st_ffn + ((size_t)bs * 2 + 0) * DFF + j0 + 4 * n); s1 = *(const f32x4*)(st_ffn + ((size_t)bs * 2 + 1) * DFF + j0 + 4 * n); }
; #pragma unroll
;                         for (int e = 0; e < 4; ++e) { const float a1 = dpp_shr1(0.f, g[e]), a2 = dpp_shr2(0.f, g[e]); p1[e] = (t >= 1) ? a1 : s1[e]; p2[e] = (t >= 2) ? a2 : (t == 1 ? s1[e] : s0[e]); }
;                         if (t >= 6) *(f32x4*)(out + O_SFFN + ((size_t)bs * 2 + (t - 6)) * DFF + j0 + 4 * n) = g;
;                     }
;                     const f32x4 gc = bb + w0 * p2 + w1 * p1 + w2 * g;
; #pragma unroll
;                     for (int e = 0; e < 4; ++e) av[e] = silu_e(gc[e]) * uu[e];
;                     if (n == 0) { keep[ai][m].x = cvt_pk_bf16(av[0], av[1]); keep[ai][m].y = cvt_pk_bf16(av[2], av[3]); }
;                     else { u32x4e w; w.x = keep[ai][m].x; w.y = keep[ai][m].y; w.z = cvt_pk_bf16(av[0], av[1]); w.w = cvt_pk_bf16(av[2], av[3]); *(u32x4e*)(ACT + act_off(r, j0)) = w; }
.LBB0_832:
	s_or_b64 exec, exec, s[20:21]
	s_and_saveexec_b64 s[20:21], s[78:79]
	v_mov_b64_e32 v[124:125], v[4:5]
	v_mov_b64_e32 v[122:123], v[2:3]
	v_mov_b32_e32 v96, v212
	v_mov_b32_e32 v97, v213
	v_mov_b32_e32 v100, v214
	v_mov_b32_e32 v101, v215
	s_or_b64 exec, exec, s[20:21]
	v_mov_b32_e32 v80, v89
	v_mov_b32_e32 v81, v95
	v_mov_b32_e32 v108, v107
	v_mov_b32_e32 v109, v125
	v_pk_mul_f32 v[108:109], v[80:81], v[108:109]
	v_fma_f32 v84, v75, v101, v79
	v_add_f32_e32 v84, v109, v84
	v_add_f32_e32 v84, v108, v84
	v_mul_f32_e32 v89, 0xbfb8aa3b, v84
	v_exp_f32_e32 v89, v89
	v_mov_b32_e32 v107, v124
	v_fma_f32 v100, v74, v100, v78
	v_mov_b32_e32 v108, v87
	v_add_f32_e32 v89, 1.0, v89
	v_rcp_f32_e32 v101, v89
	v_mov_b32_e32 v89, v94
	v_pk_mul_f32 v[94:95], v[88:89], v[106:107]
	v_mov_b32_e32 v109, v93
	v_add_f32_e32 v95, v95, v100
	v_add_f32_e32 v100, v94, v95
	v_mul_f32_e32 v94, 0xbfb8aa3b, v100
	v_exp_f32_e32 v94, v94
	v_mul_f32_e32 v84, v84, v101
	v_mul_f32_e32 v69, v69, v84
	v_mov_b32_e32 v95, v123
	v_add_f32_e32 v84, 1.0, v94
	v_mov_b32_e32 v94, v105
	v_pk_mul_f32 v[94:95], v[108:109], v[94:95]
	v_fma_f32 v87, v73, v97, v77
	v_add_f32_e32 v87, v95, v87
	v_add_f32_e32 v94, v94, v87
	v_mul_f32_e32 v87, 0xbfb8aa3b, v94
	v_exp_f32_e32 v95, v87
	v_mov_b32_e32 v87, v92
	v_mov_b32_e32 v105, v122
	v_pk_mul_f32 v[92:93], v[86:87], v[104:105]
	v_fma_f32 v96, v72, v96, v76
	v_add_f32_e32 v93, v93, v96
	v_add_f32_e32 v92, v92, v93
	v_mul_f32_e32 v93, 0xbfb8aa3b, v92
	v_exp_f32_e32 v93, v93
	v_rcp_f32_e32 v84, v84
	v_add_f32_e32 v95, 1.0, v95
	v_rcp_f32_e32 v95, v95
	v_add_f32_e32 v93, 1.0, v93
	v_rcp_f32_e32 v93, v93
	v_mul_f32_e32 v84, v100, v84
	v_mul_f32_e32 v68, v68, v84
	v_mul_f32_e32 v84, v94, v95
	v_mul_f32_e32 v67, v67, v84
	v_mul_f32_e32 v84, v92, v93
	v_mul_f32_e32 v66, v66, v84
	v_ashrrev_i32_e32 v125, 6, v184
	v_cvt_pk_bf16_f32 v122, v66, v67
	v_lshrrev_b32_e32 v66, 8, v85
	v_mad_i32_i24 v66, v66, s60, v125
	v_cvt_pk_bf16_f32 v123, v68, v69
	v_ashrrev_i32_e32 v67, 31, v66
	ds_read_b32 v84, v187 offset:64
	v_lshlrev_b64 v[66:67], 15, v[66:67]
	v_lshlrev_b32_e32 v68, 7, v217
	v_and_b32_e32 v106, 56, v216
	v_lshl_add_u64 v[66:67], s[40:41], 0, v[66:67]
	v_and_b32_e32 v68, 0x7f80, v68
	v_mov_b32_e32 v69, v179
	v_lshl_add_u64 v[66:67], v[66:67], 0, v[68:69]
	v_lshlrev_b32_e32 v110, 1, v106
	v_mov_b32_e32 v111, v179
	v_lshl_add_u64 v[66:67], v[66:67], 0, v[110:111]
	global_store_dwordx2 v[66:67], v[122:123], off offset:8
	v_add_u32_e32 v100, s74, v164
	s_waitcnt lgkmcnt(0)
	v_pk_mul_f32 v[68:69], v[56:57], v[84:85] op_sel_hi:[1,0]
	v_pk_mul_f32 v[66:67], v[54:55], v[84:85] op_sel_hi:[1,0]
	s_and_b64 vcc, exec, s[16:17]
	s_mov_b64 s[20:21], -1
	s_cbranch_vccnz .LBB0_840
	v_add_u32_e32 v85, 0xffffe000, v100
	v_ashrrev_i32_e32 v92, 3, v85
	v_mov_b32_e32 v94, 0
	v_mov_b32_e32 v95, 0
	v_mov_b32_e32 v96, 0
	v_mov_b32_e32 v97, 0
	v_mov_b32_e32 v104, 0
	v_mov_b32_e32 v105, 0
	v_mov_b32_e32 v106, 0
	v_mov_b32_e32 v107, 0
	s_and_saveexec_b64 s[20:21], s[14:15]
	s_cbranch_execz .LBB0_837
	v_mov_b64_e32 v[94:95], s[36:37]
	v_mad_i64_i32 v[94:95], s[76:77], v92, s53, v[94:95]
	v_lshl_add_u64 v[94:95], v[184:185], 2, v[94:95]
	v_add_co_u32_e32 v104, vcc, 0xa000, v94
	s_nop 1
	v_addc_co_u32_e32 v105, vcc, 0, v95, vcc
	global_load_dwordx4 v[94:97], v[94:95], off offset:16
	s_nop 0
	global_load_dwordx4 v[104:107], v[104:105], off offset:3088

; __device__ __forceinline__ unsigned cvt_pk_bf16(float lo, float hi) { unsigned r; asm volatile("v_cvt_pk_bf16_f32 %0, %1, %2" : "=v"(r) : "v"(lo), "v"(hi)); return r; }
;     __device__ __forceinline__ void operator()(const f32x4 (&acc)[2][2][4][2], const Unit& u, int wr, int wc, int fr, int fq) const {
;     ...
;                     const float rsm = RS[16 * m]; const f32x4 g = acc[ai][0][m][n] * rsm, uu = acc[ai][1][m][n] * rsm; f32x4 p1, p2, av;
;                     if (!sample) {
; #pragma unroll
;                         for (int e = 0; e < 4; ++e) { float o1, o2;
;                             if (m == 0) { o1 = bm1[e]; o2 = (fr == 0) ? bm2[e] : bm1[e]; } else { const float gp = acc[ai][0][m > 0 ? m - 1 : 0][n][e] * RS[16 * (m > 0 ? m - 1 : 0)]; o1 = dpp_ror1(gp); o2 = dpp_ror2(gp); }
;                             p1[e] = dpp_shr1(o1, g[e]); p2[e] = dpp_shr2(o2, g[e]); }
;                         if (ai == 0 && wr == 0 && m == 0 && fr < 2 && (u.pm & 7) != 0) {
;                             *(f32x4*)(fix + ((size_t)(72 + u.pm * 2 + fr)) * DFF + j0 + 4 * n) = g; *(f32x4*)(fix + ((size_t)(144 + u.pm * 2 + fr)) * DFF + j0 + 4 * n) = uu; }
;                     } else {
;                         const int t = fr & 7, bs = (r - MP) >> 3; f32x4 s0 = (f32x4){0.f, 0.f, 0.f, 0.f}, s1 = s0;
;                         if (t < 2) { s0 = *(const f32x4*)(st_ffn + ((size_t)bs * 2 + 0) * DFF + j0 + 4 * n); s1 = *(const f32x4*)(st_ffn + ((size_t)bs * 2 + 1) * DFF + j0 + 4 * n); }
; #pragma unroll
;                         for (int e = 0; e < 4; ++e) { const float a1 = dpp_shr1(0.f, g[e]), a2 = dpp_shr2(0.f, g[e]); p1[e] = (t >= 1) ? a1 : s1[e]; p2[e] = (t >= 2) ? a2 : (t == 1 ? s1[e] : s0[e]); }
;                         if (t >= 6) *(f32x4*)(out + O_SFFN + ((size_t)bs * 2 + (t - 6)) * DFF + j0 + 4 * n) = g;
;                     }
;                     const f32x4 gc = bb + w0 * p2 + w1 * p1 + w2 * g;
; #pragma unroll
;                     for (int e = 0; e < 4; ++e) av[e] = silu_e(gc[e]) * uu[e];
;                     if (n == 0) { keep[ai][m].x = cvt_pk_bf16(av[0], av[1]); keep[ai][m].y = cvt_pk_bf16(av[2], av[3]); }
;                     else { u32x4e w; w.x = keep[ai][m].x; w.y = keep[ai][m].y; w.z = cvt_pk_bf16(av[0], av[1]); w.w = cvt_pk_bf16(av[2], av[3]); *(u32x4e*)(ACT + act_off(r, j0)) = w; }
.LBB0_842:
	v_mov_b32_e32 v62, v69
	v_mov_b32_e32 v63, v95
	v_pk_mul_f32 v[62:63], v[80:81], v[62:63]
	v_fma_f32 v64, v75, v97, v79
	v_add_f32_e32 v63, v63, v64
	v_add_f32_e32 v64, v62, v63
	v_mul_f32_e32 v62, 0xbfb8aa3b, v64
	v_exp_f32_e32 v65, v62
	v_mov_b32_e32 v62, v84
	v_mov_b32_e32 v63, v84
	v_pk_mul_f32 v[60:61], v[60:61], v[62:63]
	v_add_f32_e32 v62, 1.0, v65
	v_mov_b32_e32 v69, v94
	v_rcp_f32_e32 v65, v62
	v_pk_mul_f32 v[62:63], v[88:89], v[68:69]
	v_fma_f32 v68, v74, v96, v78
	v_add_f32_e32 v63, v63, v68
	v_add_f32_e32 v68, v62, v63
	v_mul_f32_e32 v62, 0xbfb8aa3b, v68
	v_exp_f32_e32 v62, v62
	v_mul_f32_e32 v63, v64, v65
	v_mul_f32_e32 v61, v61, v63
	v_mov_b32_e32 v63, v93
	v_add_f32_e32 v62, 1.0, v62
	v_rcp_f32_e32 v64, v62
	v_mov_b32_e32 v62, v67
	v_pk_mul_f32 v[62:63], v[108:109], v[62:63]
	v_fma_f32 v65, v73, v104, v77
	v_add_f32_e32 v63, v63, v65
	v_add_f32_e32 v65, v62, v63
	v_mul_f32_e32 v62, 0xbfb8aa3b, v65
	v_mov_b32_e32 v67, v92
	v_exp_f32_e32 v69, v62
	v_pk_mul_f32 v[62:63], v[86:87], v[66:67]
	v_fma_f32 v66, v72, v101, v76
	v_add_f32_e32 v63, v63, v66
	v_add_f32_e32 v62, v62, v63
	v_mul_f32_e32 v63, 0xbfb8aa3b, v62
	v_exp_f32_e32 v63, v63
	v_add_f32_e32 v66, 1.0, v69
	v_rcp_f32_e32 v66, v66
	v_mov_b32_e32 v85, v84
	v_add_f32_e32 v63, 1.0, v63
	v_rcp_f32_e32 v63, v63
	v_pk_mul_f32 v[58:59], v[58:59], v[84:85]
	v_mul_f32_e32 v64, v68, v64
	v_mul_f32_e32 v60, v60, v64
	v_mul_f32_e32 v62, v62, v63
	v_mul_f32_e32 v64, v65, v66
	v_mul_f32_e32 v58, v58, v62
	v_mul_f32_e32 v59, v59, v64
	v_cvt_pk_bf16_f32 v120, v58, v59
	v_lshrrev_b32_e32 v58, 8, v100
	v_mad_i32_i24 v58, v58, s60, v125
	v_cvt_pk_bf16_f32 v121, v60, v61
	v_ashrrev_i32_e32 v59, 31, v58
	ds_read_b32 v68, v187 offset:128
	v_lshlrev_b64 v[58:59], 15, v[58:59]
	v_lshlrev_b32_e32 v60, 7, v164
	v_lshl_add_u64 v[58:59], s[40:41], 0, v[58:59]
	v_and_b32_e32 v60, 0x7f80, v60
	v_mov_b32_e32 v61, v179
	v_lshl_add_u64 v[58:59], v[58:59], 0, v[60:61]
	v_mov_b32_e32 v111, v179
	v_lshl_add_u64 v[58:59], v[58:59], 0, v[110:111]
	global_store_dwordx2 v[58:59], v[120:121], off offset:8
	v_add_u32_e32 v84, s74, v158
	s_waitcnt lgkmcnt(0)
	v_pk_mul_f32 v[60:61], v[44:45], v[68:69] op_sel_hi:[1,0]
	v_pk_mul_f32 v[58:59], v[42:43], v[68:69] op_sel_hi:[1,0]
	s_and_b64 vcc, exec, s[16:17]
	s_mov_b64 s[20:21], -1
	s_cbranch_vccnz .LBB0_848
	v_add_u32_e32 v62, 0xffffe000, v84
	v_ashrrev_i32_e32 v62, 3, v62
	v_mov_b32_e32 v64, 0
	v_mov_b32_e32 v65, 0
	v_mov_b32_e32 v66, 0
	v_mov_b32_e32 v67, 0
	v_mov_b32_e32 v92, 0
	v_mov_b32_e32 v93, 0
	v_mov_b32_e32 v94, 0
	v_mov_b32_e32 v95, 0
	s_and_saveexec_b64 s[20:21], s[14:15]
	s_cbranch_execz .LBB0_845
	v_mov_b64_e32 v[64:65], s[36:37]
	v_mad_i64_i32 v[64:65], s[76:77], v62, s53, v[64:65]
	v_lshl_add_u64 v[64:65], v[184:185], 2, v[64:65]
	v_add_co_u32_e32 v92, vcc, 0xa000, v64
	s_nop 1
	v_addc_co_u32_e32 v93, vcc, 0, v65, vcc
	global_load_dwordx4 v[64:67], v[64:65], off offset:16
	s_nop 0
	global_load_dwordx4 v[92:95], v[92:93], off offset:3088

; __device__ __forceinline__ unsigned cvt_pk_bf16(float lo, float hi) { unsigned r; asm volatile("v_cvt_pk_bf16_f32 %0, %1, %2" : "=v"(r) : "v"(lo), "v"(hi)); return r; }
;     __device__ __forceinline__ void operator()(const f32x4 (&acc)[2][2][4][2], const Unit& u, int wr, int wc, int fr, int fq) const {
;     ...
;                     const float rsm = RS[16 * m]; const f32x4 g = acc[ai][0][m][n] * rsm, uu = acc[ai][1][m][n] * rsm; f32x4 p1, p2, av;
;                     if (!sample) {
; #pragma unroll
;                         for (int e = 0; e < 4; ++e) { float o1, o2;
;                             if (m == 0) { o1 = bm1[e]; o2 = (fr == 0) ? bm2[e] : bm1[e]; } else { const float gp = acc[ai][0][m > 0 ? m - 1 : 0][n][e] * RS[16 * (m > 0 ? m - 1 : 0)]; o1 = dpp_ror1(gp); o2 = dpp_ror2(gp); }
;                             p1[e] = dpp_shr1(o1, g[e]); p2[e] = dpp_shr2(o2, g[e]); }
;                         if (ai == 0 && wr == 0 && m == 0 && fr < 2 && (u.pm & 7) != 0) {
;                             *(f32x4*)(fix + ((size_t)(72 + u.pm * 2 + fr)) * DFF + j0 + 4 * n) = g; *(f32x4*)(fix + ((size_t)(144 + u.pm * 2 + fr)) * DFF + j0 + 4 * n) = uu; }
;                     } else {
;                         const int t = fr & 7, bs = (r - MP) >> 3; f32x4 s0 = (f32x4){0.f, 0.f, 0.f, 0.f}, s1 = s0;
;                         if (t < 2) { s0 = *(const f32x4*)(st_ffn + ((size_t)bs * 2 + 0) * DFF + j0 + 4 * n); s1 = *(const f32x4*)(st_ffn + ((size_t)bs * 2 + 1) * DFF + j0 + 4 * n); }
; #pragma unroll
;                         for (int e = 0; e < 4; ++e) { const float a1 = dpp_shr1(0.f, g[e]), a2 = dpp_shr2(0.f, g[e]); p1[e] = (t >= 1) ? a1 : s1[e]; p2[e] = (t >= 2) ? a2 : (t == 1 ? s1[e] : s0[e]); }
;                         if (t >= 6) *(f32x4*)(out + O_SFFN + ((size_t)bs * 2 + (t - 6)) * DFF + j0 + 4 * n) = g;
;                     }
;                     const f32x4 gc = bb + w0 * p2 + w1 * p1 + w2 * g;
; #pragma unroll
;                     for (int e = 0; e < 4; ++e) av[e] = silu_e(gc[e]) * uu[e];
;                     if (n == 0) { keep[ai][m].x = cvt_pk_bf16(av[0], av[1]); keep[ai][m].y = cvt_pk_bf16(av[2], av[3]); }
;                     else { u32x4e w; w.x = keep[ai][m].x; w.y = keep[ai][m].y; w.z = cvt_pk_bf16(av[0], av[1]); w.w = cvt_pk_bf16(av[2], av[3]); *(u32x4e*)(ACT + act_off(r, j0)) = w; }
.LBB0_850:
	v_mov_b32_e32 v54, v61
	v_mov_b32_e32 v55, v65
	v_pk_mul_f32 v[54:55], v[80:81], v[54:55]
	v_fma_f32 v56, v75, v67, v79
	v_add_f32_e32 v55, v55, v56
	v_add_f32_e32 v56, v54, v55
	v_mul_f32_e32 v54, 0xbfb8aa3b, v56
	v_exp_f32_e32 v57, v54
	v_mov_b32_e32 v54, v68
	v_mov_b32_e32 v55, v68
	v_pk_mul_f32 v[52:53], v[52:53], v[54:55]
	v_add_f32_e32 v54, 1.0, v57
	v_mov_b32_e32 v61, v64
	v_rcp_f32_e32 v57, v54
	v_pk_mul_f32 v[54:55], v[88:89], v[60:61]
	v_fma_f32 v60, v74, v66, v78
	v_add_f32_e32 v55, v55, v60
	v_add_f32_e32 v60, v54, v55
	v_mul_f32_e32 v54, 0xbfb8aa3b, v60
	v_exp_f32_e32 v54, v54
	v_mul_f32_e32 v55, v56, v57
	v_mul_f32_e32 v53, v53, v55
	v_mov_b32_e32 v55, v63
	v_add_f32_e32 v54, 1.0, v54
	v_rcp_f32_e32 v56, v54
	v_mov_b32_e32 v54, v59
	v_pk_mul_f32 v[54:55], v[108:109], v[54:55]
	v_fma_f32 v57, v73, v92, v77
	v_add_f32_e32 v55, v55, v57
	v_add_f32_e32 v57, v54, v55
	v_mul_f32_e32 v54, 0xbfb8aa3b, v57
	v_mov_b32_e32 v59, v62
	v_exp_f32_e32 v61, v54
	v_pk_mul_f32 v[54:55], v[86:87], v[58:59]
	v_fma_f32 v58, v72, v85, v76
	v_add_f32_e32 v55, v55, v58
	v_add_f32_e32 v54, v54, v55
	v_mul_f32_e32 v55, 0xbfb8aa3b, v54
	v_exp_f32_e32 v55, v55
	v_add_f32_e32 v58, 1.0, v61
	v_rcp_f32_e32 v58, v58
	v_mov_b32_e32 v69, v68
	v_add_f32_e32 v55, 1.0, v55
	v_rcp_f32_e32 v55, v55
	v_pk_mul_f32 v[50:51], v[50:51], v[68:69]
	v_mul_f32_e32 v56, v60, v56
	v_mul_f32_e32 v52, v52, v56
	v_mul_f32_e32 v54, v54, v55
	v_mul_f32_e32 v56, v57, v58
	v_mul_f32_e32 v50, v50, v54
	v_mul_f32_e32 v51, v51, v56
	v_cvt_pk_bf16_f32 v116, v50, v51
	v_lshrrev_b32_e32 v50, 8, v84
	v_cvt_pk_bf16_f32 v117, v52, v53
	v_mad_i32_i24 v50, v50, s60, v125
	ds_read_b32 v60, v187 offset:192
	v_ashrrev_i32_e32 v51, 31, v50
	v_lshlrev_b64 v[50:51], 15, v[50:51]
	v_lshlrev_b32_e32 v52, 7, v158
	v_lshl_add_u64 v[50:51], s[40:41], 0, v[50:51]
	v_and_b32_e32 v52, 0x7f80, v52
	v_mov_b32_e32 v53, v179
	v_lshl_add_u64 v[50:51], v[50:51], 0, v[52:53]
	v_mov_b32_e32 v111, v179
	v_lshl_add_u64 v[50:51], v[50:51], 0, v[110:111]
	v_add_u32_e32 v62, s74, v152
	s_waitcnt lgkmcnt(0)
	v_pk_mul_f32 v[48:49], v[48:49], v[60:61] op_sel_hi:[1,0]
	v_pk_mul_f32 v[46:47], v[46:47], v[60:61] op_sel_hi:[1,0]
	s_and_b64 vcc, exec, s[16:17]
	s_mov_b64 s[20:21], -1
	global_store_dwordx2 v[50:51], v[116:117], off offset:8
	s_cbranch_vccnz .LBB0_856
	v_add_u32_e32 v50, 0xffffe000, v62
	v_ashrrev_i32_e32 v50, 3, v50
	v_mov_b32_e32 v52, 0
	v_mov_b32_e32 v53, 0
	v_mov_b32_e32 v54, 0
	v_mov_b32_e32 v55, 0
	v_mov_b32_e32 v56, 0
	v_mov_b32_e32 v57, 0
	v_mov_b32_e32 v58, 0
	v_mov_b32_e32 v59, 0
	s_and_saveexec_b64 s[20:21], s[14:15]
	s_cbranch_execz .LBB0_853
	v_mov_b64_e32 v[52:53], s[36:37]
	v_mad_i64_i32 v[52:53], s[76:77], v50, s53, v[52:53]
	v_lshl_add_u64 v[52:53], v[184:185], 2, v[52:53]
	v_add_co_u32_e32 v56, vcc, 0xa000, v52
	s_nop 1
	v_addc_co_u32_e32 v57, vcc, 0, v53, vcc
	global_load_dwordx4 v[52:55], v[52:53], off offset:16
	s_nop 0
	global_load_dwordx4 v[56:59], v[56:57], off offset:3088

; __device__ __forceinline__ unsigned cvt_pk_bf16(float lo, float hi) { unsigned r; asm volatile("v_cvt_pk_bf16_f32 %0, %1, %2" : "=v"(r) : "v"(lo), "v"(hi)); return r; }
;     __device__ __forceinline__ void operator()(const f32x4 (&acc)[2][2][4][2], const Unit& u, int wr, int wc, int fr, int fq) const {
;     ...
;                     const float rsm = RS[16 * m]; const f32x4 g = acc[ai][0][m][n] * rsm, uu = acc[ai][1][m][n] * rsm; f32x4 p1, p2, av;
;                     if (!sample) {
; #pragma unroll
;                         for (int e = 0; e < 4; ++e) { float o1, o2;
;                             if (m == 0) { o1 = bm1[e]; o2 = (fr == 0) ? bm2[e] : bm1[e]; } else { const float gp = acc[ai][0][m > 0 ? m - 1 : 0][n][e] * RS[16 * (m > 0 ? m - 1 : 0)]; o1 = dpp_ror1(gp); o2 = dpp_ror2(gp); }
;                             p1[e] = dpp_shr1(o1, g[e]); p2[e] = dpp_shr2(o2, g[e]); }
;                         if (ai == 0 && wr == 0 && m == 0 && fr < 2 && (u.pm & 7) != 0) {
;                             *(f32x4*)(fix + ((size_t)(72 + u.pm * 2 + fr)) * DFF + j0 + 4 * n) = g; *(f32x4*)(fix + ((size_t)(144 + u.pm * 2 + fr)) * DFF + j0 + 4 * n) = uu; }
;                     } else {
;                         const int t = fr & 7, bs = (r - MP) >> 3; f32x4 s0 = (f32x4){0.f, 0.f, 0.f, 0.f}, s1 = s0;
;                         if (t < 2) { s0 = *(const f32x4*)(st_ffn + ((size_t)bs * 2 + 0) * DFF + j0 + 4 * n); s1 = *(const f32x4*)(st_ffn + ((size_t)bs * 2 + 1) * DFF + j0 + 4 * n); }
; #pragma unroll
;                         for (int e = 0; e < 4; ++e) { const float a1 = dpp_shr1(0.f, g[e]), a2 = dpp_shr2(0.f, g[e]); p1[e] = (t >= 1) ? a1 : s1[e]; p2[e] = (t >= 2) ? a2 : (t == 1 ? s1[e] : s0[e]); }
;                         if (t >= 6) *(f32x4*)(out + O_SFFN + ((size_t)bs * 2 + (t - 6)) * DFF + j0 + 4 * n) = g;
;                     }
;                     const f32x4 gc = bb + w0 * p2 + w1 * p1 + w2 * g;
; #pragma unroll
;                     for (int e = 0; e < 4; ++e) av[e] = silu_e(gc[e]) * uu[e];
;                     if (n == 0) { keep[ai][m].x = cvt_pk_bf16(av[0], av[1]); keep[ai][m].y = cvt_pk_bf16(av[2], av[3]); }
;                     else { u32x4e w; w.x = keep[ai][m].x; w.y = keep[ai][m].y; w.z = cvt_pk_bf16(av[0], av[1]); w.w = cvt_pk_bf16(av[2], av[3]); *(u32x4e*)(ACT + act_off(r, j0)) = w; }
.LBB0_858:
	v_mov_b32_e32 v42, v49
	v_mov_b32_e32 v43, v53
	v_pk_mul_f32 v[42:43], v[80:81], v[42:43]
	v_fma_f32 v44, v75, v55, v79
	v_add_f32_e32 v43, v43, v44
	v_add_f32_e32 v44, v42, v43
	v_mul_f32_e32 v42, 0xbfb8aa3b, v44
	v_exp_f32_e32 v45, v42
	v_mov_b32_e32 v42, v60
	v_mov_b32_e32 v43, v60
	v_pk_mul_f32 v[40:41], v[40:41], v[42:43]
	v_add_f32_e32 v42, 1.0, v45
	v_mov_b32_e32 v49, v52
	v_rcp_f32_e32 v45, v42
	v_pk_mul_f32 v[42:43], v[88:89], v[48:49]
	v_fma_f32 v48, v74, v54, v78
	v_add_f32_e32 v43, v43, v48
	v_add_f32_e32 v48, v42, v43
	v_mul_f32_e32 v42, 0xbfb8aa3b, v48
	v_exp_f32_e32 v42, v42
	v_mul_f32_e32 v43, v44, v45
	v_mul_f32_e32 v41, v41, v43
	v_mov_b32_e32 v43, v51
	v_add_f32_e32 v42, 1.0, v42
	v_rcp_f32_e32 v44, v42
	v_mov_b32_e32 v42, v47
	v_pk_mul_f32 v[42:43], v[108:109], v[42:43]
	v_fma_f32 v45, v73, v57, v77
	v_add_f32_e32 v43, v43, v45
	v_add_f32_e32 v45, v42, v43
	v_mul_f32_e32 v42, 0xbfb8aa3b, v45
	v_mov_b32_e32 v47, v50
	v_exp_f32_e32 v49, v42
	v_pk_mul_f32 v[42:43], v[86:87], v[46:47]
	v_fma_f32 v46, v72, v56, v76
	v_add_f32_e32 v43, v43, v46
	v_add_f32_e32 v42, v42, v43
	v_mul_f32_e32 v43, 0xbfb8aa3b, v42
	v_exp_f32_e32 v43, v43
	v_add_f32_e32 v46, 1.0, v49
	v_rcp_f32_e32 v46, v46
	v_mov_b32_e32 v61, v60
	v_add_f32_e32 v43, 1.0, v43
	v_rcp_f32_e32 v43, v43
	v_pk_mul_f32 v[38:39], v[38:39], v[60:61]
	v_mul_f32_e32 v44, v48, v44
	v_mul_f32_e32 v40, v40, v44
	v_mul_f32_e32 v42, v42, v43
	v_mul_f32_e32 v44, v45, v46
	v_mul_f32_e32 v38, v38, v42
	v_mul_f32_e32 v39, v39, v44
	v_cvt_pk_bf16_f32 v104, v38, v39
	v_lshrrev_b32_e32 v38, 8, v62
	v_mad_i32_i24 v38, v38, s60, v125
	v_ashrrev_i32_e32 v39, 31, v38
	v_cvt_pk_bf16_f32 v105, v40, v41
	v_lshlrev_b64 v[38:39], 15, v[38:39]
	v_lshlrev_b32_e32 v40, 7, v152
	v_lshl_add_u64 v[38:39], s[40:41], 0, v[38:39]
	v_and_b32_e32 v40, 0x7f80, v40
	v_mov_b32_e32 v41, v179
	v_lshl_add_u64 v[38:39], v[38:39], 0, v[40:41]
	v_mov_b32_e32 v111, v179
	v_lshl_add_u64 v[38:39], v[38:39], 0, v[110:111]
	v_mov_b32_e32 v46, 0
	s_and_b64 vcc, exec, s[22:23]
	v_mov_b32_e32 v47, 0
	v_mov_b32_e32 v48, 0
	v_mov_b32_e32 v49, 0
	v_mov_b32_e32 v42, 0
	v_mov_b32_e32 v43, 0
	v_mov_b32_e32 v44, 0
	v_mov_b32_e32 v45, 0
	global_store_dwordx2 v[38:39], v[104:105], off offset:8
	s_cbranch_vccnz .LBB0_860
	ds_read_b128 v[46:49], v153 offset:16
	ds_read_b128 v[42:45], v153 offset:528

; __device__ __forceinline__ unsigned cvt_pk_bf16(float lo, float hi) { unsigned r; asm volatile("v_cvt_pk_bf16_f32 %0, %1, %2" : "=v"(r) : "v"(lo), "v"(hi)); return r; }
;     __device__ __forceinline__ void operator()(const f32x4 (&acc)[2][2][4][2], const Unit& u, int wr, int wc, int fr, int fq) const {
;     ...
;                     const float rsm = RS[16 * m]; const f32x4 g = acc[ai][0][m][n] * rsm, uu = acc[ai][1][m][n] * rsm; f32x4 p1, p2, av;
;                     if (!sample) {
; #pragma unroll
;                         for (int e = 0; e < 4; ++e) { float o1, o2;
;                             if (m == 0) { o1 = bm1[e]; o2 = (fr == 0) ? bm2[e] : bm1[e]; } else { const float gp = acc[ai][0][m > 0 ? m - 1 : 0][n][e] * RS[16 * (m > 0 ? m - 1 : 0)]; o1 = dpp_ror1(gp); o2 = dpp_ror2(gp); }
;                             p1[e] = dpp_shr1(o1, g[e]); p2[e] = dpp_shr2(o2, g[e]); }
;                         if (ai == 0 && wr == 0 && m == 0 && fr < 2 && (u.pm & 7) != 0) {
;                             *(f32x4*)(fix + ((size_t)(72 + u.pm * 2 + fr)) * DFF + j0 + 4 * n) = g; *(f32x4*)(fix + ((size_t)(144 + u.pm * 2 + fr)) * DFF + j0 + 4 * n) = uu; }
;                     } else {
;                         const int t = fr & 7, bs = (r - MP) >> 3; f32x4 s0 = (f32x4){0.f, 0.f, 0.f, 0.f}, s1 = s0;
;                         if (t < 2) { s0 = *(const f32x4*)(st_ffn + ((size_t)bs * 2 + 0) * DFF + j0 + 4 * n); s1 = *(const f32x4*)(st_ffn + ((size_t)bs * 2 + 1) * DFF + j0 + 4 * n); }
; #pragma unroll
;                         for (int e = 0; e < 4; ++e) { const float a1 = dpp_shr1(0.f, g[e]), a2 = dpp_shr2(0.f, g[e]); p1[e] = (t >= 1) ? a1 : s1[e]; p2[e] = (t >= 2) ? a2 : (t == 1 ? s1[e] : s0[e]); }
;                         if (t >= 6) *(f32x4*)(out + O_SFFN + ((size_t)bs * 2 + (t - 6)) * DFF + j0 + 4 * n) = g;
;                     }
;                     const f32x4 gc = bb + w0 * p2 + w1 * p1 + w2 * g;
; #pragma unroll
;                     for (int e = 0; e < 4; ++e) av[e] = silu_e(gc[e]) * uu[e];
;                     if (n == 0) { keep[ai][m].x = cvt_pk_bf16(av[0], av[1]); keep[ai][m].y = cvt_pk_bf16(av[2], av[3]); }
;                     else { u32x4e w; w.x = keep[ai][m].x; w.y = keep[ai][m].y; w.z = cvt_pk_bf16(av[0], av[1]); w.w = cvt_pk_bf16(av[2], av[3]); *(u32x4e*)(ACT + act_off(r, j0)) = w; }
.LBB0_868:
	v_mov_b32_e32 v42, v41
	v_mov_b32_e32 v43, v53
	v_pk_mul_f32 v[42:43], v[80:81], v[42:43]
	v_fma_f32 v41, v75, v55, v79
	v_add_f32_e32 v41, v43, v41
	v_add_f32_e32 v44, v42, v41
	v_mul_f32_e32 v41, 0xbfb8aa3b, v44
	v_exp_f32_e32 v41, v41
	v_mov_b32_e32 v42, v60
	v_mov_b32_e32 v43, v60
	v_pk_mul_f32 v[36:37], v[36:37], v[42:43]
	v_add_f32_e32 v41, 1.0, v41
	v_rcp_f32_e32 v42, v41
	v_mov_b32_e32 v41, v52
	v_pk_mul_f32 v[40:41], v[88:89], v[40:41]
	v_fma_f32 v43, v74, v54, v78
	v_add_f32_e32 v41, v41, v43
	v_add_f32_e32 v43, v40, v41
	v_mul_f32_e32 v40, 0xbfb8aa3b, v43
	v_exp_f32_e32 v40, v40
	v_mul_f32_e32 v41, v44, v42
	v_mul_f32_e32 v37, v37, v41
	v_mov_b32_e32 v41, v51
	v_add_f32_e32 v40, 1.0, v40
	v_rcp_f32_e32 v42, v40
	v_mov_b32_e32 v40, v39
	v_pk_mul_f32 v[40:41], v[108:109], v[40:41]
	v_fma_f32 v39, v73, v57, v77
	v_add_f32_e32 v39, v41, v39
	v_add_f32_e32 v40, v40, v39
	v_mul_f32_e32 v39, 0xbfb8aa3b, v40
	v_exp_f32_e32 v41, v39
	v_mov_b32_e32 v39, v50
	v_pk_mul_f32 v[38:39], v[86:87], v[38:39]
	v_fma_f32 v44, v72, v56, v76
	v_add_f32_e32 v39, v39, v44
	v_add_f32_e32 v38, v38, v39
	v_mul_f32_e32 v39, 0xbfb8aa3b, v38
	v_exp_f32_e32 v39, v39
	v_add_f32_e32 v41, 1.0, v41
	v_rcp_f32_e32 v41, v41
	v_mov_b32_e32 v61, v60
	v_add_f32_e32 v39, 1.0, v39
	v_rcp_f32_e32 v39, v39
	v_pk_mul_f32 v[34:35], v[34:35], v[60:61]
	v_mul_f32_e32 v40, v40, v41
	v_mul_f32_e32 v35, v35, v40
	v_mul_f32_e32 v38, v38, v39
	v_mul_f32_e32 v34, v34, v38
	v_cvt_pk_bf16_f32 v100, v34, v35
	v_lshrrev_b32_e32 v34, 8, v62
	v_mul_f32_e32 v42, v43, v42
	v_mad_i32_i24 v34, v34, s60, v125
	v_mul_f32_e32 v36, v36, v42
	v_cvt_pk_bf16_f32 v101, v36, v37
	v_ashrrev_i32_e32 v35, 31, v34
	ds_read_b32 v48, v150 offset:64
	v_lshlrev_b64 v[34:35], 15, v[34:35]
	v_lshlrev_b32_e32 v36, 7, v151
	v_lshl_add_u64 v[34:35], s[40:41], 0, v[34:35]
	v_and_b32_e32 v36, 0x7f80, v36
	v_mov_b32_e32 v37, v179
	v_lshl_add_u64 v[34:35], v[34:35], 0, v[36:37]
	v_mov_b32_e32 v111, v179
	v_lshl_add_u64 v[34:35], v[34:35], 0, v[110:111]
	global_store_dwordx2 v[34:35], v[100:101], off offset:8
	v_add_u32_e32 v50, s74, v142
	s_waitcnt lgkmcnt(0)
	v_pk_mul_f32 v[36:37], v[24:25], v[48:49] op_sel_hi:[1,0]
	v_pk_mul_f32 v[34:35], v[22:23], v[48:49] op_sel_hi:[1,0]
	s_and_b64 vcc, exec, s[16:17]
	s_mov_b64 s[18:19], -1
	s_cbranch_vccnz .LBB0_874
	v_add_u32_e32 v38, 0xffffe000, v50
	v_ashrrev_i32_e32 v38, 3, v38
	v_mov_b32_e32 v40, 0
	v_mov_b32_e32 v41, 0
	v_mov_b32_e32 v42, 0
	v_mov_b32_e32 v43, 0
	v_mov_b32_e32 v44, 0
	v_mov_b32_e32 v45, 0
	v_mov_b32_e32 v46, 0
	v_mov_b32_e32 v47, 0
	s_and_saveexec_b64 s[18:19], s[14:15]
	s_cbranch_execz .LBB0_871
	v_mov_b64_e32 v[40:41], s[36:37]
	v_mad_i64_i32 v[40:41], s[20:21], v38, s53, v[40:41]
	v_lshl_add_u64 v[40:41], v[184:185], 2, v[40:41]
	v_add_co_u32_e32 v44, vcc, 0xa000, v40
	s_nop 1
	v_addc_co_u32_e32 v45, vcc, 0, v41, vcc
	global_load_dwordx4 v[40:43], v[40:41], off offset:16
	s_nop 0
	global_load_dwordx4 v[44:47], v[44:45], off offset:3088

; __device__ __forceinline__ unsigned cvt_pk_bf16(float lo, float hi) { unsigned r; asm volatile("v_cvt_pk_bf16_f32 %0, %1, %2" : "=v"(r) : "v"(lo), "v"(hi)); return r; }
;     __device__ __forceinline__ void operator()(const f32x4 (&acc)[2][2][4][2], const Unit& u, int wr, int wc, int fr, int fq) const {
;     ...
;                     const float rsm = RS[16 * m]; const f32x4 g = acc[ai][0][m][n] * rsm, uu = acc[ai][1][m][n] * rsm; f32x4 p1, p2, av;
;                     if (!sample) {
; #pragma unroll
;                         for (int e = 0; e < 4; ++e) { float o1, o2;
;                             if (m == 0) { o1 = bm1[e]; o2 = (fr == 0) ? bm2[e] : bm1[e]; } else { const float gp = acc[ai][0][m > 0 ? m - 1 : 0][n][e] * RS[16 * (m > 0 ? m - 1 : 0)]; o1 = dpp_ror1(gp); o2 = dpp_ror2(gp); }
;                             p1[e] = dpp_shr1(o1, g[e]); p2[e] = dpp_shr2(o2, g[e]); }
;                         if (ai == 0 && wr == 0 && m == 0 && fr < 2 && (u.pm & 7) != 0) {
;                             *(f32x4*)(fix + ((size_t)(72 + u.pm * 2 + fr)) * DFF + j0 + 4 * n) = g; *(f32x4*)(fix + ((size_t)(144 + u.pm * 2 + fr)) * DFF + j0 + 4 * n) = uu; }
;                     } else {
;                         const int t = fr & 7, bs = (r - MP) >> 3; f32x4 s0 = (f32x4){0.f, 0.f, 0.f, 0.f}, s1 = s0;
;                         if (t < 2) { s0 = *(const f32x4*)(st_ffn + ((size_t)bs * 2 + 0) * DFF + j0 + 4 * n); s1 = *(const f32x4*)(st_ffn + ((size_t)bs * 2 + 1) * DFF + j0 + 4 * n); }
; #pragma unroll
;                         for (int e = 0; e < 4; ++e) { const float a1 = dpp_shr1(0.f, g[e]), a2 = dpp_shr2(0.f, g[e]); p1[e] = (t >= 1) ? a1 : s1[e]; p2[e] = (t >= 2) ? a2 : (t == 1 ? s1[e] : s0[e]); }
;                         if (t >= 6) *(f32x4*)(out + O_SFFN + ((size_t)bs * 2 + (t - 6)) * DFF + j0 + 4 * n) = g;
;                     }
;                     const f32x4 gc = bb + w0 * p2 + w1 * p1 + w2 * g;
; #pragma unroll
;                     for (int e = 0; e < 4; ++e) av[e] = silu_e(gc[e]) * uu[e];
;                     if (n == 0) { keep[ai][m].x = cvt_pk_bf16(av[0], av[1]); keep[ai][m].y = cvt_pk_bf16(av[2], av[3]); }
;                     else { u32x4e w; w.x = keep[ai][m].x; w.y = keep[ai][m].y; w.z = cvt_pk_bf16(av[0], av[1]); w.w = cvt_pk_bf16(av[2], av[3]); *(u32x4e*)(ACT + act_off(r, j0)) = w; }
.LBB0_876:
	v_mov_b32_e32 v30, v37
	v_mov_b32_e32 v31, v41
	v_pk_mul_f32 v[30:31], v[80:81], v[30:31]
	v_fma_f32 v32, v75, v43, v79
	v_add_f32_e32 v31, v31, v32
	v_add_f32_e32 v32, v30, v31
	v_mul_f32_e32 v30, 0xbfb8aa3b, v32
	v_exp_f32_e32 v33, v30
	v_mov_b32_e32 v30, v48
	v_mov_b32_e32 v31, v48
	v_pk_mul_f32 v[28:29], v[28:29], v[30:31]
	v_add_f32_e32 v30, 1.0, v33
	v_mov_b32_e32 v37, v40
	v_rcp_f32_e32 v33, v30
	v_pk_mul_f32 v[30:31], v[88:89], v[36:37]
	v_fma_f32 v36, v74, v42, v78
	v_add_f32_e32 v31, v31, v36
	v_add_f32_e32 v36, v30, v31
	v_mul_f32_e32 v30, 0xbfb8aa3b, v36
	v_exp_f32_e32 v30, v30
	v_mul_f32_e32 v31, v32, v33
	v_mul_f32_e32 v29, v29, v31
	v_mov_b32_e32 v31, v39
	v_add_f32_e32 v30, 1.0, v30
	v_rcp_f32_e32 v32, v30
	v_mov_b32_e32 v30, v35
	v_pk_mul_f32 v[30:31], v[108:109], v[30:31]
	v_fma_f32 v33, v73, v45, v77
	v_add_f32_e32 v31, v31, v33
	v_add_f32_e32 v33, v30, v31
	v_mul_f32_e32 v30, 0xbfb8aa3b, v33
	v_mov_b32_e32 v35, v38
	v_exp_f32_e32 v37, v30
	v_pk_mul_f32 v[30:31], v[86:87], v[34:35]
	v_fma_f32 v34, v72, v44, v76
	v_add_f32_e32 v31, v31, v34
	v_add_f32_e32 v30, v30, v31
	v_mul_f32_e32 v31, 0xbfb8aa3b, v30
	v_exp_f32_e32 v31, v31
	v_add_f32_e32 v34, 1.0, v37
	v_rcp_f32_e32 v34, v34
	v_mov_b32_e32 v49, v48
	v_add_f32_e32 v31, 1.0, v31
	v_rcp_f32_e32 v31, v31
	v_pk_mul_f32 v[26:27], v[26:27], v[48:49]
	v_mul_f32_e32 v32, v36, v32
	v_mul_f32_e32 v28, v28, v32
	v_mul_f32_e32 v30, v30, v31
	v_mul_f32_e32 v32, v33, v34
	v_mul_f32_e32 v26, v26, v30
	v_mul_f32_e32 v27, v27, v32
	v_cvt_pk_bf16_f32 v92, v26, v27
	v_lshrrev_b32_e32 v26, 8, v50
	v_mad_i32_i24 v26, v26, s60, v125
	v_cvt_pk_bf16_f32 v93, v28, v29
	v_ashrrev_i32_e32 v27, 31, v26
	ds_read_b32 v40, v150 offset:128
	v_lshlrev_b64 v[26:27], 15, v[26:27]
	v_lshlrev_b32_e32 v28, 7, v142
	v_lshl_add_u64 v[26:27], s[40:41], 0, v[26:27]
	v_and_b32_e32 v28, 0x7f80, v28
	v_mov_b32_e32 v29, v179
	v_lshl_add_u64 v[26:27], v[26:27], 0, v[28:29]
	v_mov_b32_e32 v111, v179
	v_lshl_add_u64 v[26:27], v[26:27], 0, v[110:111]
	global_store_dwordx2 v[26:27], v[92:93], off offset:8
	v_add_u32_e32 v42, s74, v113
	s_waitcnt lgkmcnt(0)
	v_pk_mul_f32 v[28:29], v[12:13], v[40:41] op_sel_hi:[1,0]
	v_pk_mul_f32 v[26:27], v[10:11], v[40:41] op_sel_hi:[1,0]
	s_and_b64 vcc, exec, s[16:17]
	s_mov_b64 s[18:19], -1
	s_cbranch_vccnz .LBB0_882
	v_add_u32_e32 v30, 0xffffe000, v42
	v_ashrrev_i32_e32 v30, 3, v30
	v_mov_b32_e32 v32, 0
	v_mov_b32_e32 v33, 0
	v_mov_b32_e32 v34, 0
	v_mov_b32_e32 v35, 0
	v_mov_b32_e32 v36, 0
	v_mov_b32_e32 v37, 0
	v_mov_b32_e32 v38, 0
	v_mov_b32_e32 v39, 0
	s_and_saveexec_b64 s[18:19], s[14:15]
	s_cbranch_execz .LBB0_879
	v_mov_b64_e32 v[32:33], s[36:37]
	v_mad_i64_i32 v[32:33], s[20:21], v30, s53, v[32:33]
	v_lshl_add_u64 v[32:33], v[184:185], 2, v[32:33]
	v_add_co_u32_e32 v36, vcc, 0xa000, v32
	s_nop 1
	v_addc_co_u32_e32 v37, vcc, 0, v33, vcc
	global_load_dwordx4 v[32:35], v[32:33], off offset:16
	s_nop 0
	global_load_dwordx4 v[36:39], v[36:37], off offset:3088

; __device__ __forceinline__ unsigned cvt_pk_bf16(float lo, float hi) { unsigned r; asm volatile("v_cvt_pk_bf16_f32 %0, %1, %2" : "=v"(r) : "v"(lo), "v"(hi)); return r; }
;     __device__ __forceinline__ void operator()(const f32x4 (&acc)[2][2][4][2], const Unit& u, int wr, int wc, int fr, int fq) const {
;     ...
;                     const float rsm = RS[16 * m]; const f32x4 g = acc[ai][0][m][n] * rsm, uu = acc[ai][1][m][n] * rsm; f32x4 p1, p2, av;
;                     if (!sample) {
; #pragma unroll
;                         for (int e = 0; e < 4; ++e) { float o1, o2;
;                             if (m == 0) { o1 = bm1[e]; o2 = (fr == 0) ? bm2[e] : bm1[e]; } else { const float gp = acc[ai][0][m > 0 ? m - 1 : 0][n][e] * RS[16 * (m > 0 ? m - 1 : 0)]; o1 = dpp_ror1(gp); o2 = dpp_ror2(gp); }
;                             p1[e] = dpp_shr1(o1, g[e]); p2[e] = dpp_shr2(o2, g[e]); }
;                         if (ai == 0 && wr == 0 && m == 0 && fr < 2 && (u.pm & 7) != 0) {
;                             *(f32x4*)(fix + ((size_t)(72 + u.pm * 2 + fr)) * DFF + j0 + 4 * n) = g; *(f32x4*)(fix + ((size_t)(144 + u.pm * 2 + fr)) * DFF + j0 + 4 * n) = uu; }
;                     } else {
;                         const int t = fr & 7, bs = (r - MP) >> 3; f32x4 s0 = (f32x4){0.f, 0.f, 0.f, 0.f}, s1 = s0;
;                         if (t < 2) { s0 = *(const f32x4*)(st_ffn + ((size_t)bs * 2 + 0) * DFF + j0 + 4 * n); s1 = *(const f32x4*)(st_ffn + ((size_t)bs * 2 + 1) * DFF + j0 + 4 * n); }
; #pragma unroll
;                         for (int e = 0; e < 4; ++e) { const float a1 = dpp_shr1(0.f, g[e]), a2 = dpp_shr2(0.f, g[e]); p1[e] = (t >= 1) ? a1 : s1[e]; p2[e] = (t >= 2) ? a2 : (t == 1 ? s1[e] : s0[e]); }
;                         if (t >= 6) *(f32x4*)(out + O_SFFN + ((size_t)bs * 2 + (t - 6)) * DFF + j0 + 4 * n) = g;
;                     }
;                     const f32x4 gc = bb + w0 * p2 + w1 * p1 + w2 * g;
; #pragma unroll
;                     for (int e = 0; e < 4; ++e) av[e] = silu_e(gc[e]) * uu[e];
;                     if (n == 0) { keep[ai][m].x = cvt_pk_bf16(av[0], av[1]); keep[ai][m].y = cvt_pk_bf16(av[2], av[3]); }
;                     else { u32x4e w; w.x = keep[ai][m].x; w.y = keep[ai][m].y; w.z = cvt_pk_bf16(av[0], av[1]); w.w = cvt_pk_bf16(av[2], av[3]); *(u32x4e*)(ACT + act_off(r, j0)) = w; }
.LBB0_884:
	v_mov_b32_e32 v22, v29
	v_mov_b32_e32 v23, v33
	v_pk_mul_f32 v[22:23], v[80:81], v[22:23]
	v_fma_f32 v24, v75, v35, v79
	v_add_f32_e32 v23, v23, v24
	v_add_f32_e32 v24, v22, v23
	v_mul_f32_e32 v22, 0xbfb8aa3b, v24
	v_exp_f32_e32 v25, v22
	v_mov_b32_e32 v22, v40
	v_mov_b32_e32 v23, v40
	v_pk_mul_f32 v[20:21], v[20:21], v[22:23]
	v_add_f32_e32 v22, 1.0, v25
	v_mov_b32_e32 v29, v32
	v_rcp_f32_e32 v25, v22
	v_pk_mul_f32 v[22:23], v[88:89], v[28:29]
	v_fma_f32 v28, v74, v34, v78
	v_add_f32_e32 v23, v23, v28
	v_add_f32_e32 v28, v22, v23
	v_mul_f32_e32 v22, 0xbfb8aa3b, v28
	v_exp_f32_e32 v22, v22
	v_mul_f32_e32 v23, v24, v25
	v_mul_f32_e32 v21, v21, v23
	v_mov_b32_e32 v23, v31
	v_add_f32_e32 v22, 1.0, v22
	v_rcp_f32_e32 v24, v22
	v_mov_b32_e32 v22, v27
	v_pk_mul_f32 v[22:23], v[108:109], v[22:23]
	v_fma_f32 v25, v73, v37, v77
	v_add_f32_e32 v23, v23, v25
	v_add_f32_e32 v25, v22, v23
	v_mul_f32_e32 v22, 0xbfb8aa3b, v25
	v_mov_b32_e32 v27, v30
	v_exp_f32_e32 v29, v22
	v_pk_mul_f32 v[22:23], v[86:87], v[26:27]
	v_fma_f32 v26, v72, v36, v76
	v_add_f32_e32 v23, v23, v26
	v_add_f32_e32 v22, v22, v23
	v_mul_f32_e32 v23, 0xbfb8aa3b, v22
	v_exp_f32_e32 v23, v23
	v_add_f32_e32 v26, 1.0, v29
	v_rcp_f32_e32 v26, v26
	v_mov_b32_e32 v41, v40
	v_add_f32_e32 v23, 1.0, v23
	v_rcp_f32_e32 v23, v23
	v_pk_mul_f32 v[18:19], v[18:19], v[40:41]
	v_mul_f32_e32 v24, v28, v24
	v_mul_f32_e32 v20, v20, v24
	v_mul_f32_e32 v22, v22, v23
	v_mul_f32_e32 v24, v25, v26
	v_mul_f32_e32 v18, v18, v22
	v_mul_f32_e32 v19, v19, v24
	v_cvt_pk_bf16_f32 v84, v18, v19
	v_lshrrev_b32_e32 v18, 8, v42
	v_cvt_pk_bf16_f32 v85, v20, v21
	v_mad_i32_i24 v18, v18, s60, v125
	ds_read_b32 v28, v150 offset:192
	v_ashrrev_i32_e32 v19, 31, v18
	v_lshlrev_b64 v[18:19], 15, v[18:19]
	v_lshlrev_b32_e32 v20, 7, v113
	v_lshl_add_u64 v[18:19], s[40:41], 0, v[18:19]
	v_and_b32_e32 v20, 0x7f80, v20
	v_mov_b32_e32 v21, v179
	v_lshl_add_u64 v[18:19], v[18:19], 0, v[20:21]
	v_mov_b32_e32 v111, v179
	v_lshl_add_u64 v[18:19], v[18:19], 0, v[110:111]
	v_add_u32_e32 v30, s74, v112
	s_waitcnt lgkmcnt(0)
	v_pk_mul_f32 v[16:17], v[16:17], v[28:29] op_sel_hi:[1,0]
	v_pk_mul_f32 v[14:15], v[14:15], v[28:29] op_sel_hi:[1,0]
	s_and_b64 vcc, exec, s[16:17]
	s_mov_b64 s[16:17], -1
	global_store_dwordx2 v[18:19], v[84:85], off offset:8
	s_cbranch_vccnz .LBB0_890
	v_add_u32_e32 v18, 0xffffe000, v30
	v_ashrrev_i32_e32 v18, 3, v18
	v_mov_b32_e32 v20, 0
	v_mov_b32_e32 v21, 0
	v_mov_b32_e32 v22, 0
	v_mov_b32_e32 v23, 0
	v_mov_b32_e32 v24, 0
	v_mov_b32_e32 v25, 0
	v_mov_b32_e32 v26, 0
	v_mov_b32_e32 v27, 0
	s_and_saveexec_b64 s[16:17], s[14:15]
	s_cbranch_execz .LBB0_887
	v_mov_b64_e32 v[20:21], s[36:37]
	v_mad_i64_i32 v[20:21], s[14:15], v18, s53, v[20:21]
	v_lshl_add_u64 v[20:21], v[184:185], 2, v[20:21]
	v_add_co_u32_e32 v24, vcc, 0xa000, v20
	s_nop 1
	v_addc_co_u32_e32 v25, vcc, 0, v21, vcc
	global_load_dwordx4 v[20:23], v[20:21], off offset:16
	s_nop 0
	global_load_dwordx4 v[24:27], v[24:25], off offset:3088

; __device__ __forceinline__ unsigned cvt_pk_bf16(float lo, float hi) { unsigned r; asm volatile("v_cvt_pk_bf16_f32 %0, %1, %2" : "=v"(r) : "v"(lo), "v"(hi)); return r; }
;     __device__ __forceinline__ void operator()(const f32x4 (&acc)[2][2][4][2], const Unit& u, int wr, int wc, int fr, int fq) const {
;     ...
;                     const float rsm = RS[16 * m]; const f32x4 g = acc[ai][0][m][n] * rsm, uu = acc[ai][1][m][n] * rsm; f32x4 p1, p2, av;
;                     if (!sample) {
; #pragma unroll
;                         for (int e = 0; e < 4; ++e) { float o1, o2;
;                             if (m == 0) { o1 = bm1[e]; o2 = (fr == 0) ? bm2[e] : bm1[e]; } else { const float gp = acc[ai][0][m > 0 ? m - 1 : 0][n][e] * RS[16 * (m > 0 ? m - 1 : 0)]; o1 = dpp_ror1(gp); o2 = dpp_ror2(gp); }
;                             p1[e] = dpp_shr1(o1, g[e]); p2[e] = dpp_shr2(o2, g[e]); }
;                         if (ai == 0 && wr == 0 && m == 0 && fr < 2 && (u.pm & 7) != 0) {
;                             *(f32x4*)(fix + ((size_t)(72 + u.pm * 2 + fr)) * DFF + j0 + 4 * n) = g; *(f32x4*)(fix + ((size_t)(144 + u.pm * 2 + fr)) * DFF + j0 + 4 * n) = uu; }
;                     } else {
;                         const int t = fr & 7, bs = (r - MP) >> 3; f32x4 s0 = (f32x4){0.f, 0.f, 0.f, 0.f}, s1 = s0;
;                         if (t < 2) { s0 = *(const f32x4*)(st_ffn + ((size_t)bs * 2 + 0) * DFF + j0 + 4 * n); s1 = *(const f32x4*)(st_ffn + ((size_t)bs * 2 + 1) * DFF + j0 + 4 * n); }
; #pragma unroll
;                         for (int e = 0; e < 4; ++e) { const float a1 = dpp_shr1(0.f, g[e]), a2 = dpp_shr2(0.f, g[e]); p1[e] = (t >= 1) ? a1 : s1[e]; p2[e] = (t >= 2) ? a2 : (t == 1 ? s1[e] : s0[e]); }
;                         if (t >= 6) *(f32x4*)(out + O_SFFN + ((size_t)bs * 2 + (t - 6)) * DFF + j0 + 4 * n) = g;
;                     }
;                     const f32x4 gc = bb + w0 * p2 + w1 * p1 + w2 * g;
; #pragma unroll
;                     for (int e = 0; e < 4; ++e) av[e] = silu_e(gc[e]) * uu[e];
;                     if (n == 0) { keep[ai][m].x = cvt_pk_bf16(av[0], av[1]); keep[ai][m].y = cvt_pk_bf16(av[2], av[3]); }
;                     else { u32x4e w; w.x = keep[ai][m].x; w.y = keep[ai][m].y; w.z = cvt_pk_bf16(av[0], av[1]); w.w = cvt_pk_bf16(av[2], av[3]); *(u32x4e*)(ACT + act_off(r, j0)) = w; }
.LBB0_892:
	v_mov_b32_e32 v10, v17
	v_mov_b32_e32 v11, v21
	v_pk_mul_f32 v[10:11], v[80:81], v[10:11]
	v_fma_f32 v12, v75, v23, v79
	v_add_f32_e32 v11, v11, v12
	v_add_f32_e32 v12, v10, v11
	v_mul_f32_e32 v10, 0xbfb8aa3b, v12
	v_exp_f32_e32 v13, v10
	v_mov_b32_e32 v10, v28
	v_mov_b32_e32 v11, v28
	v_pk_mul_f32 v[8:9], v[8:9], v[10:11]
	v_add_f32_e32 v10, 1.0, v13
	v_mov_b32_e32 v17, v20
	v_rcp_f32_e32 v13, v10
	v_pk_mul_f32 v[10:11], v[88:89], v[16:17]
	v_fma_f32 v16, v74, v22, v78
	v_add_f32_e32 v11, v11, v16
	v_add_f32_e32 v16, v10, v11
	v_mul_f32_e32 v10, 0xbfb8aa3b, v16
	v_exp_f32_e32 v10, v10
	v_mul_f32_e32 v11, v12, v13
	v_mul_f32_e32 v9, v9, v11
	v_mov_b32_e32 v11, v19
	v_add_f32_e32 v10, 1.0, v10
	v_rcp_f32_e32 v12, v10
	v_mov_b32_e32 v10, v15
	v_pk_mul_f32 v[10:11], v[108:109], v[10:11]
	v_fma_f32 v13, v73, v25, v77
	v_add_f32_e32 v11, v11, v13
	v_add_f32_e32 v13, v10, v11
	v_mul_f32_e32 v10, 0xbfb8aa3b, v13
	v_mov_b32_e32 v15, v18
	v_exp_f32_e32 v17, v10
	v_pk_mul_f32 v[10:11], v[86:87], v[14:15]
	v_fmac_f32_e32 v76, v72, v24
	v_add_f32_e32 v11, v11, v76
	v_add_f32_e32 v10, v10, v11
	v_mul_f32_e32 v11, 0xbfb8aa3b, v10
	v_exp_f32_e32 v11, v11
	v_add_f32_e32 v14, 1.0, v17
	v_rcp_f32_e32 v14, v14
	v_mov_b32_e32 v29, v28
	v_add_f32_e32 v11, 1.0, v11
	v_rcp_f32_e32 v11, v11
	v_pk_mul_f32 v[6:7], v[6:7], v[28:29]
	v_mul_f32_e32 v12, v16, v12
	v_mul_f32_e32 v8, v8, v12
	v_mul_f32_e32 v10, v10, v11
	v_mul_f32_e32 v12, v13, v14
	v_mul_f32_e32 v6, v6, v10
	v_mul_f32_e32 v7, v7, v12
	v_cvt_pk_bf16_f32 v72, v6, v7
	v_lshrrev_b32_e32 v6, 8, v30
	v_mad_i32_i24 v6, v6, s60, v125
	v_ashrrev_i32_e32 v7, 31, v6
	v_cvt_pk_bf16_f32 v73, v8, v9
	v_lshlrev_b64 v[6:7], 15, v[6:7]
	v_lshlrev_b32_e32 v8, 7, v112
	v_lshl_add_u64 v[6:7], s[40:41], 0, v[6:7]
	v_and_b32_e32 v178, 0x7f80, v8
	v_lshl_add_u64 v[6:7], v[6:7], 0, v[178:179]
	v_mov_b32_e32 v111, v179
	v_lshl_add_u64 v[6:7], v[6:7], 0, v[110:111]
	s_andn2_b64 vcc, exec, s[68:69]
	s_mov_b64 s[6:7], -1
	global_store_dwordx2 v[6:7], v[72:73], off offset:8
	s_cbranch_vccnz .LBB0_705
	s_andn2_b64 vcc, exec, s[38:39]
	s_cbranch_vccnz .LBB0_704
	s_barrier
	s_branch .LBB0_704
